# FF2 prompt-tile owner pre-pass: register ring widened to 13 quads (Gn vector loads deferred until after the pre-pass)
# baseline (speedup 1.0000x reference)
.Lfq_LBB0_1414:
	v_readlane_b32 s36, v243, 58
	v_readlane_b32 s37, v243, 59
	v_mov_b32_e32 v155, 0
	s_andn2_b64 vcc, exec, s[80:81]
	v_cndmask_b32_e64 v128, 0, 1, s[36:37]
	v_cmp_ne_u32_e64 s[80:81], 1, v128
	v_mov_b32_e32 v154, 0
	v_mov_b32_e32 v153, 0
	v_mov_b32_e32 v152, 0
	v_mov_b32_e32 v159, 0
	v_mov_b32_e32 v158, 0
	v_mov_b32_e32 v157, 0
	v_mov_b32_e32 v156, 0
	v_mov_b32_e32 v147, 0
	v_mov_b32_e32 v146, 0
	v_mov_b32_e32 v145, 0
	v_mov_b32_e32 v144, 0
	v_mov_b32_e32 v151, 0
	v_mov_b32_e32 v150, 0
	v_mov_b32_e32 v149, 0
	v_mov_b32_e32 v148, 0
	v_mov_b32_e32 v131, 0
	v_mov_b32_e32 v130, 0
	s_waitcnt lgkmcnt(0)
	v_mov_b32_e32 v129, 0
	v_mov_b32_e32 v128, 0
	v_mov_b32_e32 v135, 0
	v_mov_b32_e32 v134, 0
	v_mov_b32_e32 v133, 0
	v_mov_b32_e32 v132, 0
	v_mov_b32_e32 v139, 0
	v_mov_b32_e32 v138, 0
	v_mov_b32_e32 v137, 0
	v_mov_b32_e32 v136, 0
	v_mov_b32_e32 v143, 0
	v_mov_b32_e32 v142, 0
	v_mov_b32_e32 v141, 0
	v_mov_b32_e32 v140, 0
	s_cbranch_vccnz .Lfq_LBB0_1420
	s_ashr_i32 s35, s31, 3
	v_readlane_b32 s36, v243, 57
	s_add_i32 s36, s35, s36
	s_ashr_i32 s37, s36, 31
	s_mul_i32 s38, s36, 0xc000
	s_mul_hi_i32 s35, s36, 0xc000
	s_add_u32 s38, s14, s38
	s_addc_u32 s39, s15, s35
	v_lshlrev_b64 v[130:131], 2, v[200:201]
	v_lshl_add_u64 v[128:129], s[38:39], 0, v[130:131]
	global_load_dwordx4 v[144:147], v[128:129], off offset:16
	global_load_dwordx4 v[148:151], v[128:129], off
	v_lshl_add_u64 v[130:131], s[16:17], 0, v[130:131]
	s_lshl_b64 s[36:37], s[36:37], 12
	v_lshl_add_u64 v[160:161], v[130:131], 0, s[36:37]
	v_mov_b32_e32 v131, 0
	s_and_b64 vcc, exec, s[80:81]
	v_mov_b32_e32 v140, 0
	v_mov_b32_e32 v141, 0
	v_mov_b32_e32 v142, 0
	v_mov_b32_e32 v143, 0
	v_mov_b32_e32 v136, 0
	v_mov_b32_e32 v137, 0
	v_mov_b32_e32 v138, 0
	v_mov_b32_e32 v139, 0
	s_cbranch_vccnz .Lfq_LBB0_1417
.Lfq_LBB0_1417:
	global_load_dwordx4 v[156:159], v[128:129], off offset:512
	global_load_dwordx4 v[152:155], v[128:129], off offset:528
	s_and_b64 vcc, exec, s[80:81]
	v_mov_b32_e32 v130, 0
	v_mov_b32_e32 v129, 0
	v_mov_b32_e32 v128, 0
	v_mov_b32_e32 v135, 0
	v_mov_b32_e32 v134, 0
	v_mov_b32_e32 v133, 0
	v_mov_b32_e32 v132, 0
	s_cbranch_vccnz .Lfq_LBB0_1419
.Lfq_LBB0_1419:
	s_mov_b32 s38, 0xc000

.Lfq_LBB0_1423:
	v_lshlrev_b32_e32 v203, 12, v204
	v_lshl_add_u32 v203, v200, 2, v203
	v_lshlrev_b32_e32 v205, 2, v194
	s_cmp_eq_u32 s30, 1
	s_cbranch_scc1 .Lfq_np1
	s_cmp_eq_u32 s30, 2
	s_cbranch_scc1 .Lfq_np2
	s_add_u32 s42, s62, 0x0
	s_addc_u32 s43, s63, 0
	global_load_dwordx4 v[128:131], v205, s[42:43] sc0 sc1
	s_add_u32 s98, s62, 0x1000
	s_addc_u32 s99, s63, 0
	global_load_dwordx4 v[132:135], v205, s[98:99] sc0 sc1
	s_add_u32 s42, s62, 0x400
	s_addc_u32 s43, s63, 0
	global_load_dwordx4 v[136:139], v205, s[42:43] sc0 sc1
	s_add_u32 s98, s62, 0x1400
	s_addc_u32 s99, s63, 0
	global_load_dwordx4 v[140:143], v205, s[98:99] sc0 sc1
	s_add_u32 s42, s62, 0x800
	s_addc_u32 s43, s63, 0
	global_load_dwordx4 v[160:163], v205, s[42:43] sc0 sc1
	s_add_u32 s98, s62, 0x1800
	s_addc_u32 s99, s63, 0
	global_load_dwordx4 v[164:167], v205, s[98:99] sc0 sc1
	s_add_u32 s42, s62, 0xc00
	s_addc_u32 s43, s63, 0
	global_load_dwordx4 v[168:171], v205, s[42:43] sc0 sc1
	s_add_u32 s98, s62, 0x1c00
	s_addc_u32 s99, s63, 0
	global_load_dwordx4 v[172:175], v205, s[98:99] sc0 sc1
	s_add_u32 s42, s62, 0x2000
	s_addc_u32 s43, s63, 0
	global_load_dwordx4 v[176:179], v205, s[42:43] sc0 sc1
	s_add_u32 s98, s62, 0x3000
	s_addc_u32 s99, s63, 0
	global_load_dwordx4 v[180:183], v205, s[98:99] sc0 sc1
	s_add_u32 s42, s62, 0x2400
	s_addc_u32 s43, s63, 0
	global_load_dwordx4 v[206:209], v205, s[42:43] sc0 sc1
	s_add_u32 s98, s62, 0x3400
	s_addc_u32 s99, s63, 0
	global_load_dwordx4 v[210:213], v205, s[98:99] sc0 sc1
	s_add_u32 s42, s62, 0x2800
	s_addc_u32 s43, s63, 0
	global_load_dwordx4 v[236:239], v205, s[42:43] sc0 sc1
	s_waitcnt vmcnt(12)
	v_lshlrev_b32_e32 v240, 16, v128
	v_and_b32_e32 v241, 0xffff0000, v128
	v_pk_add_f32 v[124:125], v[124:125], v[240:241]
	v_lshlrev_b32_e32 v240, 16, v129
	v_and_b32_e32 v241, 0xffff0000, v129
	v_pk_add_f32 v[126:127], v[126:127], v[240:241]
	v_lshlrev_b32_e32 v240, 16, v130
	v_and_b32_e32 v241, 0xffff0000, v130
	v_pk_add_f32 v[120:121], v[120:121], v[240:241]
	v_lshlrev_b32_e32 v240, 16, v131
	v_and_b32_e32 v241, 0xffff0000, v131
	v_pk_add_f32 v[122:123], v[122:123], v[240:241]
	s_add_u32 s98, s62, 0x3800
	s_addc_u32 s99, s63, 0
	global_load_dwordx4 v[128:131], v205, s[98:99] sc0 sc1
	s_waitcnt vmcnt(12)
	v_lshlrev_b32_e32 v240, 16, v132
	v_and_b32_e32 v241, 0xffff0000, v132
	v_pk_add_f32 v[92:93], v[92:93], v[240:241]
	v_lshlrev_b32_e32 v240, 16, v133
	v_and_b32_e32 v241, 0xffff0000, v133
	v_pk_add_f32 v[94:95], v[94:95], v[240:241]
	v_lshlrev_b32_e32 v240, 16, v134
	v_and_b32_e32 v241, 0xffff0000, v134
	v_pk_add_f32 v[88:89], v[88:89], v[240:241]
	v_lshlrev_b32_e32 v240, 16, v135
	v_and_b32_e32 v241, 0xffff0000, v135
	v_pk_add_f32 v[90:91], v[90:91], v[240:241]
	s_add_u32 s42, s62, 0x2c00
	s_addc_u32 s43, s63, 0
	global_load_dwordx4 v[132:135], v205, s[42:43] sc0 sc1
	s_waitcnt vmcnt(12)
	v_lshlrev_b32_e32 v240, 16, v136
	v_and_b32_e32 v241, 0xffff0000, v136
	v_pk_add_f32 v[116:117], v[116:117], v[240:241]
	v_lshlrev_b32_e32 v240, 16, v137
	v_and_b32_e32 v241, 0xffff0000, v137
	v_pk_add_f32 v[118:119], v[118:119], v[240:241]
	v_lshlrev_b32_e32 v240, 16, v138
	v_and_b32_e32 v241, 0xffff0000, v138
	v_pk_add_f32 v[112:113], v[112:113], v[240:241]
	v_lshlrev_b32_e32 v240, 16, v139
	v_and_b32_e32 v241, 0xffff0000, v139
	v_pk_add_f32 v[114:115], v[114:115], v[240:241]
	s_add_u32 s98, s62, 0x3c00
	s_addc_u32 s99, s63, 0
	global_load_dwordx4 v[136:139], v205, s[98:99] sc0 sc1
	s_waitcnt vmcnt(12)
	v_lshlrev_b32_e32 v240, 16, v140
	v_and_b32_e32 v241, 0xffff0000, v140
	v_pk_add_f32 v[84:85], v[84:85], v[240:241]
	v_lshlrev_b32_e32 v240, 16, v141
	v_and_b32_e32 v241, 0xffff0000, v141
	v_pk_add_f32 v[86:87], v[86:87], v[240:241]
	v_lshlrev_b32_e32 v240, 16, v142
	v_and_b32_e32 v241, 0xffff0000, v142
	v_pk_add_f32 v[80:81], v[80:81], v[240:241]
	v_lshlrev_b32_e32 v240, 16, v143
	v_and_b32_e32 v241, 0xffff0000, v143
	v_pk_add_f32 v[82:83], v[82:83], v[240:241]
	s_add_u32 s42, s62, 0x20000
	s_addc_u32 s43, s63, 0
	global_load_dwordx4 v[140:143], v205, s[42:43] sc0 sc1
	s_waitcnt vmcnt(12)
	v_lshlrev_b32_e32 v240, 16, v160
	v_and_b32_e32 v241, 0xffff0000, v160
	v_pk_add_f32 v[108:109], v[108:109], v[240:241]
	v_lshlrev_b32_e32 v240, 16, v161
	v_and_b32_e32 v241, 0xffff0000, v161
	v_pk_add_f32 v[110:111], v[110:111], v[240:241]
	v_lshlrev_b32_e32 v240, 16, v162
	v_and_b32_e32 v241, 0xffff0000, v162
	v_pk_add_f32 v[104:105], v[104:105], v[240:241]
	v_lshlrev_b32_e32 v240, 16, v163
	v_and_b32_e32 v241, 0xffff0000, v163
	v_pk_add_f32 v[106:107], v[106:107], v[240:241]
	s_add_u32 s98, s62, 0x21000
	s_addc_u32 s99, s63, 0
	global_load_dwordx4 v[160:163], v205, s[98:99] sc0 sc1
	s_waitcnt vmcnt(12)
	v_lshlrev_b32_e32 v240, 16, v164
	v_and_b32_e32 v241, 0xffff0000, v164
	v_pk_add_f32 v[76:77], v[76:77], v[240:241]
	v_lshlrev_b32_e32 v240, 16, v165
	v_and_b32_e32 v241, 0xffff0000, v165
	v_pk_add_f32 v[78:79], v[78:79], v[240:241]
	v_lshlrev_b32_e32 v240, 16, v166
	v_and_b32_e32 v241, 0xffff0000, v166
	v_pk_add_f32 v[72:73], v[72:73], v[240:241]
	v_lshlrev_b32_e32 v240, 16, v167
	v_and_b32_e32 v241, 0xffff0000, v167
	v_pk_add_f32 v[74:75], v[74:75], v[240:241]
	s_add_u32 s42, s62, 0x20400
	s_addc_u32 s43, s63, 0
	global_load_dwordx4 v[164:167], v205, s[42:43] sc0 sc1
	s_waitcnt vmcnt(12)
	v_lshlrev_b32_e32 v240, 16, v168
	v_and_b32_e32 v241, 0xffff0000, v168
	v_pk_add_f32 v[100:101], v[100:101], v[240:241]
	v_lshlrev_b32_e32 v240, 16, v169
	v_and_b32_e32 v241, 0xffff0000, v169
	v_pk_add_f32 v[102:103], v[102:103], v[240:241]
	v_lshlrev_b32_e32 v240, 16, v170
	v_and_b32_e32 v241, 0xffff0000, v170
	v_pk_add_f32 v[96:97], v[96:97], v[240:241]
	v_lshlrev_b32_e32 v240, 16, v171
	v_and_b32_e32 v241, 0xffff0000, v171
	v_pk_add_f32 v[98:99], v[98:99], v[240:241]
	s_add_u32 s98, s62, 0x21400
	s_addc_u32 s99, s63, 0
	global_load_dwordx4 v[168:171], v205, s[98:99] sc0 sc1
	s_waitcnt vmcnt(12)
	v_lshlrev_b32_e32 v240, 16, v172
	v_and_b32_e32 v241, 0xffff0000, v172
	v_pk_add_f32 v[68:69], v[68:69], v[240:241]
	v_lshlrev_b32_e32 v240, 16, v173
	v_and_b32_e32 v241, 0xffff0000, v173
	v_pk_add_f32 v[70:71], v[70:71], v[240:241]
	v_lshlrev_b32_e32 v240, 16, v174
	v_and_b32_e32 v241, 0xffff0000, v174
	v_pk_add_f32 v[64:65], v[64:65], v[240:241]
	v_lshlrev_b32_e32 v240, 16, v175
	v_and_b32_e32 v241, 0xffff0000, v175
	v_pk_add_f32 v[66:67], v[66:67], v[240:241]
	s_add_u32 s42, s62, 0x20800
	s_addc_u32 s43, s63, 0
	global_load_dwordx4 v[172:175], v205, s[42:43] sc0 sc1
	s_waitcnt vmcnt(12)
	v_lshlrev_b32_e32 v240, 16, v176
	v_and_b32_e32 v241, 0xffff0000, v176
	v_pk_add_f32 v[60:61], v[60:61], v[240:241]
	v_lshlrev_b32_e32 v240, 16, v177
	v_and_b32_e32 v241, 0xffff0000, v177
	v_pk_add_f32 v[62:63], v[62:63], v[240:241]
	v_lshlrev_b32_e32 v240, 16, v178
	v_and_b32_e32 v241, 0xffff0000, v178
	v_pk_add_f32 v[56:57], v[56:57], v[240:241]
	v_lshlrev_b32_e32 v240, 16, v179
	v_and_b32_e32 v241, 0xffff0000, v179
	v_pk_add_f32 v[58:59], v[58:59], v[240:241]
	s_add_u32 s98, s62, 0x21800
	s_addc_u32 s99, s63, 0
	global_load_dwordx4 v[176:179], v205, s[98:99] sc0 sc1
	s_waitcnt vmcnt(12)
	v_lshlrev_b32_e32 v240, 16, v180
	v_and_b32_e32 v241, 0xffff0000, v180
	v_pk_add_f32 v[28:29], v[28:29], v[240:241]
	v_lshlrev_b32_e32 v240, 16, v181
	v_and_b32_e32 v241, 0xffff0000, v181
	v_pk_add_f32 v[30:31], v[30:31], v[240:241]
	v_lshlrev_b32_e32 v240, 16, v182
	v_and_b32_e32 v241, 0xffff0000, v182
	v_pk_add_f32 v[24:25], v[24:25], v[240:241]
	v_lshlrev_b32_e32 v240, 16, v183
	v_and_b32_e32 v241, 0xffff0000, v183
	v_pk_add_f32 v[26:27], v[26:27], v[240:241]
	s_add_u32 s42, s62, 0x20c00
	s_addc_u32 s43, s63, 0
	global_load_dwordx4 v[180:183], v205, s[42:43] sc0 sc1
	s_waitcnt vmcnt(12)
	v_lshlrev_b32_e32 v240, 16, v206
	v_and_b32_e32 v241, 0xffff0000, v206
	v_pk_add_f32 v[52:53], v[52:53], v[240:241]
	v_lshlrev_b32_e32 v240, 16, v207
	v_and_b32_e32 v241, 0xffff0000, v207
	v_pk_add_f32 v[54:55], v[54:55], v[240:241]
	v_lshlrev_b32_e32 v240, 16, v208
	v_and_b32_e32 v241, 0xffff0000, v208
	v_pk_add_f32 v[48:49], v[48:49], v[240:241]
	v_lshlrev_b32_e32 v240, 16, v209
	v_and_b32_e32 v241, 0xffff0000, v209
	v_pk_add_f32 v[50:51], v[50:51], v[240:241]
	s_add_u32 s98, s62, 0x21c00
	s_addc_u32 s99, s63, 0
	global_load_dwordx4 v[206:209], v205, s[98:99] sc0 sc1
	s_waitcnt vmcnt(12)
	v_lshlrev_b32_e32 v240, 16, v210
	v_and_b32_e32 v241, 0xffff0000, v210
	v_pk_add_f32 v[20:21], v[20:21], v[240:241]
	v_lshlrev_b32_e32 v240, 16, v211
	v_and_b32_e32 v241, 0xffff0000, v211
	v_pk_add_f32 v[22:23], v[22:23], v[240:241]
	v_lshlrev_b32_e32 v240, 16, v212
	v_and_b32_e32 v241, 0xffff0000, v212
	v_pk_add_f32 v[16:17], v[16:17], v[240:241]
	v_lshlrev_b32_e32 v240, 16, v213
	v_and_b32_e32 v241, 0xffff0000, v213
	v_pk_add_f32 v[18:19], v[18:19], v[240:241]
	s_add_u32 s42, s62, 0x22000
	s_addc_u32 s43, s63, 0
	global_load_dwordx4 v[210:213], v205, s[42:43] sc0 sc1
	s_waitcnt vmcnt(12)
	v_lshlrev_b32_e32 v240, 16, v236
	v_and_b32_e32 v241, 0xffff0000, v236
	v_pk_add_f32 v[44:45], v[44:45], v[240:241]
	v_lshlrev_b32_e32 v240, 16, v237
	v_and_b32_e32 v241, 0xffff0000, v237
	v_pk_add_f32 v[46:47], v[46:47], v[240:241]
	v_lshlrev_b32_e32 v240, 16, v238
	v_and_b32_e32 v241, 0xffff0000, v238
	v_pk_add_f32 v[40:41], v[40:41], v[240:241]
	v_lshlrev_b32_e32 v240, 16, v239
	v_and_b32_e32 v241, 0xffff0000, v239
	v_pk_add_f32 v[42:43], v[42:43], v[240:241]
	s_add_u32 s98, s62, 0x23000
	s_addc_u32 s99, s63, 0
	global_load_dwordx4 v[236:239], v205, s[98:99] sc0 sc1
	s_waitcnt vmcnt(12)
	v_lshlrev_b32_e32 v240, 16, v128
	v_and_b32_e32 v241, 0xffff0000, v128
	v_pk_add_f32 v[12:13], v[12:13], v[240:241]
	v_lshlrev_b32_e32 v240, 16, v129
	v_and_b32_e32 v241, 0xffff0000, v129
	v_pk_add_f32 v[14:15], v[14:15], v[240:241]
	v_lshlrev_b32_e32 v240, 16, v130
	v_and_b32_e32 v241, 0xffff0000, v130
	v_pk_add_f32 v[8:9], v[8:9], v[240:241]
	v_lshlrev_b32_e32 v240, 16, v131
	v_and_b32_e32 v241, 0xffff0000, v131
	v_pk_add_f32 v[10:11], v[10:11], v[240:241]
	s_add_u32 s42, s62, 0x22400
	s_addc_u32 s43, s63, 0
	global_load_dwordx4 v[128:131], v205, s[42:43] sc0 sc1
	s_waitcnt vmcnt(12)
	v_lshlrev_b32_e32 v240, 16, v132
	v_and_b32_e32 v241, 0xffff0000, v132
	v_pk_add_f32 v[36:37], v[36:37], v[240:241]
	v_lshlrev_b32_e32 v240, 16, v133
	v_and_b32_e32 v241, 0xffff0000, v133
	v_pk_add_f32 v[38:39], v[38:39], v[240:241]
	v_lshlrev_b32_e32 v240, 16, v134
	v_and_b32_e32 v241, 0xffff0000, v134
	v_pk_add_f32 v[32:33], v[32:33], v[240:241]
	v_lshlrev_b32_e32 v240, 16, v135
	v_and_b32_e32 v241, 0xffff0000, v135
	v_pk_add_f32 v[34:35], v[34:35], v[240:241]
	s_add_u32 s98, s62, 0x23400
	s_addc_u32 s99, s63, 0
	global_load_dwordx4 v[132:135], v205, s[98:99] sc0 sc1
	s_waitcnt vmcnt(12)
	v_lshlrev_b32_e32 v240, 16, v136
	v_and_b32_e32 v241, 0xffff0000, v136
	v_pk_add_f32 v[4:5], v[4:5], v[240:241]
	v_lshlrev_b32_e32 v240, 16, v137
	v_and_b32_e32 v241, 0xffff0000, v137
	v_pk_add_f32 v[6:7], v[6:7], v[240:241]
	v_lshlrev_b32_e32 v240, 16, v138
	v_and_b32_e32 v241, 0xffff0000, v138
	v_pk_add_f32 v[0:1], v[0:1], v[240:241]
	v_lshlrev_b32_e32 v240, 16, v139
	v_and_b32_e32 v241, 0xffff0000, v139
	v_pk_add_f32 v[2:3], v[2:3], v[240:241]
	s_add_u32 s42, s62, 0x22800
	s_addc_u32 s43, s63, 0
	global_load_dwordx4 v[136:139], v205, s[42:43] sc0 sc1
	s_waitcnt vmcnt(12)
	v_lshlrev_b32_e32 v240, 16, v140
	v_and_b32_e32 v241, 0xffff0000, v140
	v_pk_add_f32 v[124:125], v[124:125], v[240:241]
	v_lshlrev_b32_e32 v240, 16, v141
	v_and_b32_e32 v241, 0xffff0000, v141
	v_pk_add_f32 v[126:127], v[126:127], v[240:241]
	v_lshlrev_b32_e32 v240, 16, v142
	v_and_b32_e32 v241, 0xffff0000, v142
	v_pk_add_f32 v[120:121], v[120:121], v[240:241]
	v_lshlrev_b32_e32 v240, 16, v143
	v_and_b32_e32 v241, 0xffff0000, v143
	v_pk_add_f32 v[122:123], v[122:123], v[240:241]
	s_add_u32 s98, s62, 0x23800
	s_addc_u32 s99, s63, 0
	global_load_dwordx4 v[140:143], v205, s[98:99] sc0 sc1
	s_waitcnt vmcnt(12)
	v_lshlrev_b32_e32 v240, 16, v160
	v_and_b32_e32 v241, 0xffff0000, v160
	v_pk_add_f32 v[92:93], v[92:93], v[240:241]
	v_lshlrev_b32_e32 v240, 16, v161
	v_and_b32_e32 v241, 0xffff0000, v161
	v_pk_add_f32 v[94:95], v[94:95], v[240:241]
	v_lshlrev_b32_e32 v240, 16, v162
	v_and_b32_e32 v241, 0xffff0000, v162
	v_pk_add_f32 v[88:89], v[88:89], v[240:241]
	v_lshlrev_b32_e32 v240, 16, v163
	v_and_b32_e32 v241, 0xffff0000, v163
	v_pk_add_f32 v[90:91], v[90:91], v[240:241]
	s_add_u32 s42, s62, 0x22c00
	s_addc_u32 s43, s63, 0
	global_load_dwordx4 v[160:163], v205, s[42:43] sc0 sc1
	s_waitcnt vmcnt(12)
	v_lshlrev_b32_e32 v240, 16, v164
	v_and_b32_e32 v241, 0xffff0000, v164
	v_pk_add_f32 v[116:117], v[116:117], v[240:241]
	v_lshlrev_b32_e32 v240, 16, v165
	v_and_b32_e32 v241, 0xffff0000, v165
	v_pk_add_f32 v[118:119], v[118:119], v[240:241]
	v_lshlrev_b32_e32 v240, 16, v166
	v_and_b32_e32 v241, 0xffff0000, v166
	v_pk_add_f32 v[112:113], v[112:113], v[240:241]
	v_lshlrev_b32_e32 v240, 16, v167
	v_and_b32_e32 v241, 0xffff0000, v167
	v_pk_add_f32 v[114:115], v[114:115], v[240:241]
	s_add_u32 s98, s62, 0x23c00
	s_addc_u32 s99, s63, 0
	global_load_dwordx4 v[164:167], v205, s[98:99] sc0 sc1
	s_waitcnt vmcnt(12)
	v_lshlrev_b32_e32 v240, 16, v168
	v_and_b32_e32 v241, 0xffff0000, v168
	v_pk_add_f32 v[84:85], v[84:85], v[240:241]
	v_lshlrev_b32_e32 v240, 16, v169
	v_and_b32_e32 v241, 0xffff0000, v169
	v_pk_add_f32 v[86:87], v[86:87], v[240:241]
	v_lshlrev_b32_e32 v240, 16, v170
	v_and_b32_e32 v241, 0xffff0000, v170
	v_pk_add_f32 v[80:81], v[80:81], v[240:241]
	v_lshlrev_b32_e32 v240, 16, v171
	v_and_b32_e32 v241, 0xffff0000, v171
	v_pk_add_f32 v[82:83], v[82:83], v[240:241]
	s_add_u32 s42, s62, 0x40000
	s_addc_u32 s43, s63, 0
	global_load_dwordx4 v[168:171], v205, s[42:43] sc0 sc1
	s_waitcnt vmcnt(12)
	v_lshlrev_b32_e32 v240, 16, v172
	v_and_b32_e32 v241, 0xffff0000, v172
	v_pk_add_f32 v[108:109], v[108:109], v[240:241]
	v_lshlrev_b32_e32 v240, 16, v173
	v_and_b32_e32 v241, 0xffff0000, v173
	v_pk_add_f32 v[110:111], v[110:111], v[240:241]
	v_lshlrev_b32_e32 v240, 16, v174
	v_and_b32_e32 v241, 0xffff0000, v174
	v_pk_add_f32 v[104:105], v[104:105], v[240:241]
	v_lshlrev_b32_e32 v240, 16, v175
	v_and_b32_e32 v241, 0xffff0000, v175
	v_pk_add_f32 v[106:107], v[106:107], v[240:241]
	s_add_u32 s98, s62, 0x41000
	s_addc_u32 s99, s63, 0
	global_load_dwordx4 v[172:175], v205, s[98:99] sc0 sc1
	s_waitcnt vmcnt(12)
	v_lshlrev_b32_e32 v240, 16, v176
	v_and_b32_e32 v241, 0xffff0000, v176
	v_pk_add_f32 v[76:77], v[76:77], v[240:241]
	v_lshlrev_b32_e32 v240, 16, v177
	v_and_b32_e32 v241, 0xffff0000, v177
	v_pk_add_f32 v[78:79], v[78:79], v[240:241]
	v_lshlrev_b32_e32 v240, 16, v178
	v_and_b32_e32 v241, 0xffff0000, v178
	v_pk_add_f32 v[72:73], v[72:73], v[240:241]
	v_lshlrev_b32_e32 v240, 16, v179
	v_and_b32_e32 v241, 0xffff0000, v179
	v_pk_add_f32 v[74:75], v[74:75], v[240:241]
	s_add_u32 s42, s62, 0x40400
	s_addc_u32 s43, s63, 0
	global_load_dwordx4 v[176:179], v205, s[42:43] sc0 sc1
	s_waitcnt vmcnt(12)
	v_lshlrev_b32_e32 v240, 16, v180
	v_and_b32_e32 v241, 0xffff0000, v180
	v_pk_add_f32 v[100:101], v[100:101], v[240:241]
	v_lshlrev_b32_e32 v240, 16, v181
	v_and_b32_e32 v241, 0xffff0000, v181
	v_pk_add_f32 v[102:103], v[102:103], v[240:241]
	v_lshlrev_b32_e32 v240, 16, v182
	v_and_b32_e32 v241, 0xffff0000, v182
	v_pk_add_f32 v[96:97], v[96:97], v[240:241]
	v_lshlrev_b32_e32 v240, 16, v183
	v_and_b32_e32 v241, 0xffff0000, v183
	v_pk_add_f32 v[98:99], v[98:99], v[240:241]
	s_add_u32 s98, s62, 0x41400
	s_addc_u32 s99, s63, 0
	global_load_dwordx4 v[180:183], v205, s[98:99] sc0 sc1
	s_waitcnt vmcnt(12)
	v_lshlrev_b32_e32 v240, 16, v206
	v_and_b32_e32 v241, 0xffff0000, v206
	v_pk_add_f32 v[68:69], v[68:69], v[240:241]
	v_lshlrev_b32_e32 v240, 16, v207
	v_and_b32_e32 v241, 0xffff0000, v207
	v_pk_add_f32 v[70:71], v[70:71], v[240:241]
	v_lshlrev_b32_e32 v240, 16, v208
	v_and_b32_e32 v241, 0xffff0000, v208
	v_pk_add_f32 v[64:65], v[64:65], v[240:241]
	v_lshlrev_b32_e32 v240, 16, v209
	v_and_b32_e32 v241, 0xffff0000, v209
	v_pk_add_f32 v[66:67], v[66:67], v[240:241]
	s_add_u32 s42, s62, 0x40800
	s_addc_u32 s43, s63, 0
	global_load_dwordx4 v[206:209], v205, s[42:43] sc0 sc1
	s_waitcnt vmcnt(12)
	v_lshlrev_b32_e32 v240, 16, v210
	v_and_b32_e32 v241, 0xffff0000, v210
	v_pk_add_f32 v[60:61], v[60:61], v[240:241]
	v_lshlrev_b32_e32 v240, 16, v211
	v_and_b32_e32 v241, 0xffff0000, v211
	v_pk_add_f32 v[62:63], v[62:63], v[240:241]
	v_lshlrev_b32_e32 v240, 16, v212
	v_and_b32_e32 v241, 0xffff0000, v212
	v_pk_add_f32 v[56:57], v[56:57], v[240:241]
	v_lshlrev_b32_e32 v240, 16, v213
	v_and_b32_e32 v241, 0xffff0000, v213
	v_pk_add_f32 v[58:59], v[58:59], v[240:241]
	s_add_u32 s98, s62, 0x41800
	s_addc_u32 s99, s63, 0
	global_load_dwordx4 v[210:213], v205, s[98:99] sc0 sc1
	s_waitcnt vmcnt(12)
	v_lshlrev_b32_e32 v240, 16, v236
	v_and_b32_e32 v241, 0xffff0000, v236
	v_pk_add_f32 v[28:29], v[28:29], v[240:241]
	v_lshlrev_b32_e32 v240, 16, v237
	v_and_b32_e32 v241, 0xffff0000, v237
	v_pk_add_f32 v[30:31], v[30:31], v[240:241]
	v_lshlrev_b32_e32 v240, 16, v238
	v_and_b32_e32 v241, 0xffff0000, v238
	v_pk_add_f32 v[24:25], v[24:25], v[240:241]
	v_lshlrev_b32_e32 v240, 16, v239
	v_and_b32_e32 v241, 0xffff0000, v239
	v_pk_add_f32 v[26:27], v[26:27], v[240:241]
	s_add_u32 s42, s62, 0x40c00
	s_addc_u32 s43, s63, 0
	global_load_dwordx4 v[236:239], v205, s[42:43] sc0 sc1
	s_waitcnt vmcnt(12)
	v_lshlrev_b32_e32 v240, 16, v128
	v_and_b32_e32 v241, 0xffff0000, v128
	v_pk_add_f32 v[52:53], v[52:53], v[240:241]
	v_lshlrev_b32_e32 v240, 16, v129
	v_and_b32_e32 v241, 0xffff0000, v129
	v_pk_add_f32 v[54:55], v[54:55], v[240:241]
	v_lshlrev_b32_e32 v240, 16, v130
	v_and_b32_e32 v241, 0xffff0000, v130
	v_pk_add_f32 v[48:49], v[48:49], v[240:241]
	v_lshlrev_b32_e32 v240, 16, v131
	v_and_b32_e32 v241, 0xffff0000, v131
	v_pk_add_f32 v[50:51], v[50:51], v[240:241]
	s_add_u32 s98, s62, 0x41c00
	s_addc_u32 s99, s63, 0
	global_load_dwordx4 v[128:131], v205, s[98:99] sc0 sc1
	s_waitcnt vmcnt(12)
	v_lshlrev_b32_e32 v240, 16, v132
	v_and_b32_e32 v241, 0xffff0000, v132
	v_pk_add_f32 v[20:21], v[20:21], v[240:241]
	v_lshlrev_b32_e32 v240, 16, v133
	v_and_b32_e32 v241, 0xffff0000, v133
	v_pk_add_f32 v[22:23], v[22:23], v[240:241]
	v_lshlrev_b32_e32 v240, 16, v134
	v_and_b32_e32 v241, 0xffff0000, v134
	v_pk_add_f32 v[16:17], v[16:17], v[240:241]
	v_lshlrev_b32_e32 v240, 16, v135
	v_and_b32_e32 v241, 0xffff0000, v135
	v_pk_add_f32 v[18:19], v[18:19], v[240:241]
	s_add_u32 s42, s62, 0x42000
	s_addc_u32 s43, s63, 0
	global_load_dwordx4 v[132:135], v205, s[42:43] sc0 sc1
	s_waitcnt vmcnt(12)
	v_lshlrev_b32_e32 v240, 16, v136
	v_and_b32_e32 v241, 0xffff0000, v136
	v_pk_add_f32 v[44:45], v[44:45], v[240:241]
	v_lshlrev_b32_e32 v240, 16, v137
	v_and_b32_e32 v241, 0xffff0000, v137
	v_pk_add_f32 v[46:47], v[46:47], v[240:241]
	v_lshlrev_b32_e32 v240, 16, v138
	v_and_b32_e32 v241, 0xffff0000, v138
	v_pk_add_f32 v[40:41], v[40:41], v[240:241]
	v_lshlrev_b32_e32 v240, 16, v139
	v_and_b32_e32 v241, 0xffff0000, v139
	v_pk_add_f32 v[42:43], v[42:43], v[240:241]
	s_add_u32 s98, s62, 0x43000
	s_addc_u32 s99, s63, 0
	global_load_dwordx4 v[136:139], v205, s[98:99] sc0 sc1
	s_waitcnt vmcnt(12)
	v_lshlrev_b32_e32 v240, 16, v140
	v_and_b32_e32 v241, 0xffff0000, v140
	v_pk_add_f32 v[12:13], v[12:13], v[240:241]
	v_lshlrev_b32_e32 v240, 16, v141
	v_and_b32_e32 v241, 0xffff0000, v141
	v_pk_add_f32 v[14:15], v[14:15], v[240:241]
	v_lshlrev_b32_e32 v240, 16, v142
	v_and_b32_e32 v241, 0xffff0000, v142
	v_pk_add_f32 v[8:9], v[8:9], v[240:241]
	v_lshlrev_b32_e32 v240, 16, v143
	v_and_b32_e32 v241, 0xffff0000, v143
	v_pk_add_f32 v[10:11], v[10:11], v[240:241]
	s_add_u32 s42, s62, 0x42400
	s_addc_u32 s43, s63, 0
	global_load_dwordx4 v[140:143], v205, s[42:43] sc0 sc1
	s_waitcnt vmcnt(12)
	v_lshlrev_b32_e32 v240, 16, v160
	v_and_b32_e32 v241, 0xffff0000, v160
	v_pk_add_f32 v[36:37], v[36:37], v[240:241]
	v_lshlrev_b32_e32 v240, 16, v161
	v_and_b32_e32 v241, 0xffff0000, v161
	v_pk_add_f32 v[38:39], v[38:39], v[240:241]
	v_lshlrev_b32_e32 v240, 16, v162
	v_and_b32_e32 v241, 0xffff0000, v162
	v_pk_add_f32 v[32:33], v[32:33], v[240:241]
	v_lshlrev_b32_e32 v240, 16, v163
	v_and_b32_e32 v241, 0xffff0000, v163
	v_pk_add_f32 v[34:35], v[34:35], v[240:241]
	s_add_u32 s98, s62, 0x43400
	s_addc_u32 s99, s63, 0
	global_load_dwordx4 v[160:163], v205, s[98:99] sc0 sc1
	s_waitcnt vmcnt(12)
	v_lshlrev_b32_e32 v240, 16, v164
	v_and_b32_e32 v241, 0xffff0000, v164
	v_pk_add_f32 v[4:5], v[4:5], v[240:241]
	v_lshlrev_b32_e32 v240, 16, v165
	v_and_b32_e32 v241, 0xffff0000, v165
	v_pk_add_f32 v[6:7], v[6:7], v[240:241]
	v_lshlrev_b32_e32 v240, 16, v166
	v_and_b32_e32 v241, 0xffff0000, v166
	v_pk_add_f32 v[0:1], v[0:1], v[240:241]
	v_lshlrev_b32_e32 v240, 16, v167
	v_and_b32_e32 v241, 0xffff0000, v167
	v_pk_add_f32 v[2:3], v[2:3], v[240:241]
	s_add_u32 s42, s62, 0x42800
	s_addc_u32 s43, s63, 0
	global_load_dwordx4 v[164:167], v205, s[42:43] sc0 sc1
	s_waitcnt vmcnt(12)
	v_lshlrev_b32_e32 v240, 16, v168
	v_and_b32_e32 v241, 0xffff0000, v168
	v_pk_add_f32 v[124:125], v[124:125], v[240:241]
	v_lshlrev_b32_e32 v240, 16, v169
	v_and_b32_e32 v241, 0xffff0000, v169
	v_pk_add_f32 v[126:127], v[126:127], v[240:241]
	v_lshlrev_b32_e32 v240, 16, v170
	v_and_b32_e32 v241, 0xffff0000, v170
	v_pk_add_f32 v[120:121], v[120:121], v[240:241]
	v_lshlrev_b32_e32 v240, 16, v171
	v_and_b32_e32 v241, 0xffff0000, v171
	v_pk_add_f32 v[122:123], v[122:123], v[240:241]
	s_add_u32 s98, s62, 0x43800
	s_addc_u32 s99, s63, 0
	global_load_dwordx4 v[168:171], v205, s[98:99] sc0 sc1
	s_waitcnt vmcnt(12)
	v_lshlrev_b32_e32 v240, 16, v172
	v_and_b32_e32 v241, 0xffff0000, v172
	v_pk_add_f32 v[92:93], v[92:93], v[240:241]
	v_lshlrev_b32_e32 v240, 16, v173
	v_and_b32_e32 v241, 0xffff0000, v173
	v_pk_add_f32 v[94:95], v[94:95], v[240:241]
	v_lshlrev_b32_e32 v240, 16, v174
	v_and_b32_e32 v241, 0xffff0000, v174
	v_pk_add_f32 v[88:89], v[88:89], v[240:241]
	v_lshlrev_b32_e32 v240, 16, v175
	v_and_b32_e32 v241, 0xffff0000, v175
	v_pk_add_f32 v[90:91], v[90:91], v[240:241]
	s_add_u32 s42, s62, 0x42c00
	s_addc_u32 s43, s63, 0
	global_load_dwordx4 v[172:175], v205, s[42:43] sc0 sc1
	s_waitcnt vmcnt(12)
	v_lshlrev_b32_e32 v240, 16, v176
	v_and_b32_e32 v241, 0xffff0000, v176
	v_pk_add_f32 v[116:117], v[116:117], v[240:241]
	v_lshlrev_b32_e32 v240, 16, v177
	v_and_b32_e32 v241, 0xffff0000, v177
	v_pk_add_f32 v[118:119], v[118:119], v[240:241]
	v_lshlrev_b32_e32 v240, 16, v178
	v_and_b32_e32 v241, 0xffff0000, v178
	v_pk_add_f32 v[112:113], v[112:113], v[240:241]
	v_lshlrev_b32_e32 v240, 16, v179
	v_and_b32_e32 v241, 0xffff0000, v179
	v_pk_add_f32 v[114:115], v[114:115], v[240:241]
	s_add_u32 s98, s62, 0x43c00
	s_addc_u32 s99, s63, 0
	global_load_dwordx4 v[176:179], v205, s[98:99] sc0 sc1
	s_waitcnt vmcnt(12)
	v_lshlrev_b32_e32 v240, 16, v180
	v_and_b32_e32 v241, 0xffff0000, v180
	v_pk_add_f32 v[84:85], v[84:85], v[240:241]
	v_lshlrev_b32_e32 v240, 16, v181
	v_and_b32_e32 v241, 0xffff0000, v181
	v_pk_add_f32 v[86:87], v[86:87], v[240:241]
	v_lshlrev_b32_e32 v240, 16, v182
	v_and_b32_e32 v241, 0xffff0000, v182
	v_pk_add_f32 v[80:81], v[80:81], v[240:241]
	v_lshlrev_b32_e32 v240, 16, v183
	v_and_b32_e32 v241, 0xffff0000, v183
	v_pk_add_f32 v[82:83], v[82:83], v[240:241]
	s_add_u32 s42, s10, 0x0
	s_addc_u32 s43, s11, 0
	global_load_dwordx4 v[180:183], v203, s[42:43]
	s_waitcnt vmcnt(12)
	v_lshlrev_b32_e32 v240, 16, v206
	v_and_b32_e32 v241, 0xffff0000, v206
	v_pk_add_f32 v[108:109], v[108:109], v[240:241]
	v_lshlrev_b32_e32 v240, 16, v207
	v_and_b32_e32 v241, 0xffff0000, v207
	v_pk_add_f32 v[110:111], v[110:111], v[240:241]
	v_lshlrev_b32_e32 v240, 16, v208
	v_and_b32_e32 v241, 0xffff0000, v208
	v_pk_add_f32 v[104:105], v[104:105], v[240:241]
	v_lshlrev_b32_e32 v240, 16, v209
	v_and_b32_e32 v241, 0xffff0000, v209
	v_pk_add_f32 v[106:107], v[106:107], v[240:241]
	s_add_u32 s98, s10, 0x0
	s_addc_u32 s99, s11, 0
	global_load_dwordx4 v[206:209], v203, s[98:99] offset:16
	s_waitcnt vmcnt(12)
	v_lshlrev_b32_e32 v240, 16, v210
	v_and_b32_e32 v241, 0xffff0000, v210
	v_pk_add_f32 v[76:77], v[76:77], v[240:241]
	v_lshlrev_b32_e32 v240, 16, v211
	v_and_b32_e32 v241, 0xffff0000, v211
	v_pk_add_f32 v[78:79], v[78:79], v[240:241]
	v_lshlrev_b32_e32 v240, 16, v212
	v_and_b32_e32 v241, 0xffff0000, v212
	v_pk_add_f32 v[72:73], v[72:73], v[240:241]
	v_lshlrev_b32_e32 v240, 16, v213
	v_and_b32_e32 v241, 0xffff0000, v213
	v_pk_add_f32 v[74:75], v[74:75], v[240:241]
	s_add_u32 s42, s10, 0x200
	s_addc_u32 s43, s11, 0
	global_load_dwordx4 v[210:213], v203, s[42:43]
	s_waitcnt vmcnt(12)
	v_lshlrev_b32_e32 v240, 16, v236
	v_and_b32_e32 v241, 0xffff0000, v236
	v_pk_add_f32 v[100:101], v[100:101], v[240:241]
	v_lshlrev_b32_e32 v240, 16, v237
	v_and_b32_e32 v241, 0xffff0000, v237
	v_pk_add_f32 v[102:103], v[102:103], v[240:241]
	v_lshlrev_b32_e32 v240, 16, v238
	v_and_b32_e32 v241, 0xffff0000, v238
	v_pk_add_f32 v[96:97], v[96:97], v[240:241]
	v_lshlrev_b32_e32 v240, 16, v239
	v_and_b32_e32 v241, 0xffff0000, v239
	v_pk_add_f32 v[98:99], v[98:99], v[240:241]
	s_add_u32 s98, s10, 0x200
	s_addc_u32 s99, s11, 0
	global_load_dwordx4 v[236:239], v203, s[98:99] offset:16
	s_waitcnt vmcnt(12)
	v_lshlrev_b32_e32 v240, 16, v128
	v_and_b32_e32 v241, 0xffff0000, v128
	v_pk_add_f32 v[68:69], v[68:69], v[240:241]
	v_lshlrev_b32_e32 v240, 16, v129
	v_and_b32_e32 v241, 0xffff0000, v129
	v_pk_add_f32 v[70:71], v[70:71], v[240:241]
	v_lshlrev_b32_e32 v240, 16, v130
	v_and_b32_e32 v241, 0xffff0000, v130
	v_pk_add_f32 v[64:65], v[64:65], v[240:241]
	v_lshlrev_b32_e32 v240, 16, v131
	v_and_b32_e32 v241, 0xffff0000, v131
	v_pk_add_f32 v[66:67], v[66:67], v[240:241]
	s_add_u32 s42, s10, 0x10000
	s_addc_u32 s43, s11, 0
	global_load_dwordx4 v[128:131], v203, s[42:43]
	s_waitcnt vmcnt(12)
	v_lshlrev_b32_e32 v240, 16, v132
	v_and_b32_e32 v241, 0xffff0000, v132
	v_pk_add_f32 v[60:61], v[60:61], v[240:241]
	v_lshlrev_b32_e32 v240, 16, v133
	v_and_b32_e32 v241, 0xffff0000, v133
	v_pk_add_f32 v[62:63], v[62:63], v[240:241]
	v_lshlrev_b32_e32 v240, 16, v134
	v_and_b32_e32 v241, 0xffff0000, v134
	v_pk_add_f32 v[56:57], v[56:57], v[240:241]
	v_lshlrev_b32_e32 v240, 16, v135
	v_and_b32_e32 v241, 0xffff0000, v135
	v_pk_add_f32 v[58:59], v[58:59], v[240:241]
	s_add_u32 s98, s10, 0x10000
	s_addc_u32 s99, s11, 0
	global_load_dwordx4 v[132:135], v203, s[98:99] offset:16
	s_waitcnt vmcnt(12)
	v_lshlrev_b32_e32 v240, 16, v136
	v_and_b32_e32 v241, 0xffff0000, v136
	v_pk_add_f32 v[28:29], v[28:29], v[240:241]
	v_lshlrev_b32_e32 v240, 16, v137
	v_and_b32_e32 v241, 0xffff0000, v137
	v_pk_add_f32 v[30:31], v[30:31], v[240:241]
	v_lshlrev_b32_e32 v240, 16, v138
	v_and_b32_e32 v241, 0xffff0000, v138
	v_pk_add_f32 v[24:25], v[24:25], v[240:241]
	v_lshlrev_b32_e32 v240, 16, v139
	v_and_b32_e32 v241, 0xffff0000, v139
	v_pk_add_f32 v[26:27], v[26:27], v[240:241]
	s_add_u32 s42, s10, 0x10200
	s_addc_u32 s43, s11, 0
	global_load_dwordx4 v[136:139], v203, s[42:43]
	s_waitcnt vmcnt(12)
	v_lshlrev_b32_e32 v240, 16, v140
	v_and_b32_e32 v241, 0xffff0000, v140
	v_pk_add_f32 v[52:53], v[52:53], v[240:241]
	v_lshlrev_b32_e32 v240, 16, v141
	v_and_b32_e32 v241, 0xffff0000, v141
	v_pk_add_f32 v[54:55], v[54:55], v[240:241]
	v_lshlrev_b32_e32 v240, 16, v142
	v_and_b32_e32 v241, 0xffff0000, v142
	v_pk_add_f32 v[48:49], v[48:49], v[240:241]
	v_lshlrev_b32_e32 v240, 16, v143
	v_and_b32_e32 v241, 0xffff0000, v143
	v_pk_add_f32 v[50:51], v[50:51], v[240:241]
	s_add_u32 s98, s10, 0x10200
	s_addc_u32 s99, s11, 0
	global_load_dwordx4 v[140:143], v203, s[98:99] offset:16
	s_waitcnt vmcnt(12)
	v_lshlrev_b32_e32 v240, 16, v160
	v_and_b32_e32 v241, 0xffff0000, v160
	v_pk_add_f32 v[20:21], v[20:21], v[240:241]
	v_lshlrev_b32_e32 v240, 16, v161
	v_and_b32_e32 v241, 0xffff0000, v161
	v_pk_add_f32 v[22:23], v[22:23], v[240:241]
	v_lshlrev_b32_e32 v240, 16, v162
	v_and_b32_e32 v241, 0xffff0000, v162
	v_pk_add_f32 v[16:17], v[16:17], v[240:241]
	v_lshlrev_b32_e32 v240, 16, v163
	v_and_b32_e32 v241, 0xffff0000, v163
	v_pk_add_f32 v[18:19], v[18:19], v[240:241]
	s_add_u32 s42, s10, 0x20000
	s_addc_u32 s43, s11, 0
	global_load_dwordx4 v[160:163], v203, s[42:43]
	s_waitcnt vmcnt(12)
	v_lshlrev_b32_e32 v240, 16, v164
	v_and_b32_e32 v241, 0xffff0000, v164
	v_pk_add_f32 v[44:45], v[44:45], v[240:241]
	v_lshlrev_b32_e32 v240, 16, v165
	v_and_b32_e32 v241, 0xffff0000, v165
	v_pk_add_f32 v[46:47], v[46:47], v[240:241]
	v_lshlrev_b32_e32 v240, 16, v166
	v_and_b32_e32 v241, 0xffff0000, v166
	v_pk_add_f32 v[40:41], v[40:41], v[240:241]
	v_lshlrev_b32_e32 v240, 16, v167
	v_and_b32_e32 v241, 0xffff0000, v167
	v_pk_add_f32 v[42:43], v[42:43], v[240:241]
	s_add_u32 s98, s10, 0x20000
	s_addc_u32 s99, s11, 0
	global_load_dwordx4 v[164:167], v203, s[98:99] offset:16
	s_waitcnt vmcnt(12)
	v_lshlrev_b32_e32 v240, 16, v168
	v_and_b32_e32 v241, 0xffff0000, v168
	v_pk_add_f32 v[12:13], v[12:13], v[240:241]
	v_lshlrev_b32_e32 v240, 16, v169
	v_and_b32_e32 v241, 0xffff0000, v169
	v_pk_add_f32 v[14:15], v[14:15], v[240:241]
	v_lshlrev_b32_e32 v240, 16, v170
	v_and_b32_e32 v241, 0xffff0000, v170
	v_pk_add_f32 v[8:9], v[8:9], v[240:241]
	v_lshlrev_b32_e32 v240, 16, v171
	v_and_b32_e32 v241, 0xffff0000, v171
	v_pk_add_f32 v[10:11], v[10:11], v[240:241]
	s_add_u32 s42, s10, 0x20200
	s_addc_u32 s43, s11, 0
	global_load_dwordx4 v[168:171], v203, s[42:43]
	s_waitcnt vmcnt(12)
	v_lshlrev_b32_e32 v240, 16, v172
	v_and_b32_e32 v241, 0xffff0000, v172
	v_pk_add_f32 v[36:37], v[36:37], v[240:241]
	v_lshlrev_b32_e32 v240, 16, v173
	v_and_b32_e32 v241, 0xffff0000, v173
	v_pk_add_f32 v[38:39], v[38:39], v[240:241]
	v_lshlrev_b32_e32 v240, 16, v174
	v_and_b32_e32 v241, 0xffff0000, v174
	v_pk_add_f32 v[32:33], v[32:33], v[240:241]
	v_lshlrev_b32_e32 v240, 16, v175
	v_and_b32_e32 v241, 0xffff0000, v175
	v_pk_add_f32 v[34:35], v[34:35], v[240:241]
	s_add_u32 s98, s10, 0x20200
	s_addc_u32 s99, s11, 0
	global_load_dwordx4 v[172:175], v203, s[98:99] offset:16
	s_waitcnt vmcnt(12)
	v_lshlrev_b32_e32 v240, 16, v176
	v_and_b32_e32 v241, 0xffff0000, v176
	v_pk_add_f32 v[4:5], v[4:5], v[240:241]
	v_lshlrev_b32_e32 v240, 16, v177
	v_and_b32_e32 v241, 0xffff0000, v177
	v_pk_add_f32 v[6:7], v[6:7], v[240:241]
	v_lshlrev_b32_e32 v240, 16, v178
	v_and_b32_e32 v241, 0xffff0000, v178
	v_pk_add_f32 v[0:1], v[0:1], v[240:241]
	v_lshlrev_b32_e32 v240, 16, v179
	v_and_b32_e32 v241, 0xffff0000, v179
	v_pk_add_f32 v[2:3], v[2:3], v[240:241]
	s_add_u32 s42, s10, 0x30000
	s_addc_u32 s43, s11, 0
	global_load_dwordx4 v[176:179], v203, s[42:43]
	s_waitcnt vmcnt(12)
	v_pk_fma_f32 v[124:125], v[148:149], v[124:125], v[180:181]
	v_pk_fma_f32 v[126:127], v[150:151], v[126:127], v[182:183]
	s_add_u32 s98, s10, 0x0
	s_addc_u32 s99, s11, 0
	global_store_dwordx4 v203, v[124:127], s[98:99]
	s_add_u32 s42, s10, 0x30000
	s_addc_u32 s43, s11, 0
	global_load_dwordx4 v[180:183], v203, s[42:43] offset:16
	s_waitcnt vmcnt(13)
	v_pk_fma_f32 v[120:121], v[144:145], v[120:121], v[206:207]
	v_pk_fma_f32 v[122:123], v[146:147], v[122:123], v[208:209]
	s_add_u32 s98, s10, 0x0
	s_addc_u32 s99, s11, 0
	global_store_dwordx4 v203, v[120:123], s[98:99] offset:16
	s_add_u32 s42, s10, 0x30200
	s_addc_u32 s43, s11, 0
	global_load_dwordx4 v[206:209], v203, s[42:43]
	s_waitcnt vmcnt(14)
	v_pk_fma_f32 v[92:93], v[156:157], v[92:93], v[210:211]
	v_pk_fma_f32 v[94:95], v[158:159], v[94:95], v[212:213]
	s_add_u32 s98, s10, 0x200
	s_addc_u32 s99, s11, 0
	global_store_dwordx4 v203, v[92:95], s[98:99]
	s_add_u32 s42, s10, 0x30200
	s_addc_u32 s43, s11, 0
	global_load_dwordx4 v[210:213], v203, s[42:43] offset:16
	s_waitcnt vmcnt(15)
	v_pk_fma_f32 v[88:89], v[152:153], v[88:89], v[236:237]
	v_pk_fma_f32 v[90:91], v[154:155], v[90:91], v[238:239]
	s_add_u32 s98, s10, 0x200
	s_addc_u32 s99, s11, 0
	global_store_dwordx4 v203, v[88:91], s[98:99] offset:16
	s_add_u32 s42, s10, 0x80000
	s_addc_u32 s43, s11, 0
	global_load_dwordx4 v[236:239], v203, s[42:43]
	s_waitcnt vmcnt(16)
	v_pk_fma_f32 v[116:117], v[148:149], v[116:117], v[128:129]
	v_pk_fma_f32 v[118:119], v[150:151], v[118:119], v[130:131]
	s_add_u32 s98, s10, 0x10000
	s_addc_u32 s99, s11, 0
	global_store_dwordx4 v203, v[116:119], s[98:99]
	s_add_u32 s42, s10, 0x80000
	s_addc_u32 s43, s11, 0
	global_load_dwordx4 v[128:131], v203, s[42:43] offset:16
	s_waitcnt vmcnt(17)
	v_pk_fma_f32 v[112:113], v[144:145], v[112:113], v[132:133]
	v_pk_fma_f32 v[114:115], v[146:147], v[114:115], v[134:135]
	s_add_u32 s98, s10, 0x10000
	s_addc_u32 s99, s11, 0
	global_store_dwordx4 v203, v[112:115], s[98:99] offset:16
	s_add_u32 s42, s10, 0x80200
	s_addc_u32 s43, s11, 0
	global_load_dwordx4 v[132:135], v203, s[42:43]
	s_waitcnt vmcnt(18)
	v_pk_fma_f32 v[84:85], v[156:157], v[84:85], v[136:137]
	v_pk_fma_f32 v[86:87], v[158:159], v[86:87], v[138:139]
	s_add_u32 s98, s10, 0x10200
	s_addc_u32 s99, s11, 0
	global_store_dwordx4 v203, v[84:87], s[98:99]
	s_add_u32 s42, s10, 0x80200
	s_addc_u32 s43, s11, 0
	global_load_dwordx4 v[136:139], v203, s[42:43] offset:16
	s_waitcnt vmcnt(19)
	v_pk_fma_f32 v[80:81], v[152:153], v[80:81], v[140:141]
	v_pk_fma_f32 v[82:83], v[154:155], v[82:83], v[142:143]
	s_add_u32 s98, s10, 0x10200
	s_addc_u32 s99, s11, 0
	global_store_dwordx4 v203, v[80:83], s[98:99] offset:16
	s_add_u32 s42, s10, 0x90000
	s_addc_u32 s43, s11, 0
	global_load_dwordx4 v[140:143], v203, s[42:43]
	s_waitcnt vmcnt(20)
	v_pk_fma_f32 v[108:109], v[148:149], v[108:109], v[160:161]
	v_pk_fma_f32 v[110:111], v[150:151], v[110:111], v[162:163]
	s_add_u32 s98, s10, 0x20000
	s_addc_u32 s99, s11, 0
	global_store_dwordx4 v203, v[108:111], s[98:99]
	s_add_u32 s42, s10, 0x90000
	s_addc_u32 s43, s11, 0
	global_load_dwordx4 v[160:163], v203, s[42:43] offset:16
	s_waitcnt vmcnt(21)
	v_pk_fma_f32 v[104:105], v[144:145], v[104:105], v[164:165]
	v_pk_fma_f32 v[106:107], v[146:147], v[106:107], v[166:167]
	s_add_u32 s98, s10, 0x20000
	s_addc_u32 s99, s11, 0
	global_store_dwordx4 v203, v[104:107], s[98:99] offset:16
	s_add_u32 s42, s10, 0x90200
	s_addc_u32 s43, s11, 0
	global_load_dwordx4 v[164:167], v203, s[42:43]
	s_waitcnt vmcnt(22)
	v_pk_fma_f32 v[76:77], v[156:157], v[76:77], v[168:169]
	v_pk_fma_f32 v[78:79], v[158:159], v[78:79], v[170:171]
	s_add_u32 s98, s10, 0x20200
	s_addc_u32 s99, s11, 0
	global_store_dwordx4 v203, v[76:79], s[98:99]
	s_add_u32 s42, s10, 0x90200
	s_addc_u32 s43, s11, 0
	global_load_dwordx4 v[168:171], v203, s[42:43] offset:16
	s_waitcnt vmcnt(23)
	v_pk_fma_f32 v[72:73], v[152:153], v[72:73], v[172:173]
	v_pk_fma_f32 v[74:75], v[154:155], v[74:75], v[174:175]
	s_add_u32 s98, s10, 0x20200
	s_addc_u32 s99, s11, 0
	global_store_dwordx4 v203, v[72:75], s[98:99] offset:16
	s_add_u32 s42, s10, 0xa0000
	s_addc_u32 s43, s11, 0
	global_load_dwordx4 v[172:175], v203, s[42:43]
	s_waitcnt vmcnt(24)
	v_pk_fma_f32 v[100:101], v[148:149], v[100:101], v[176:177]
	v_pk_fma_f32 v[102:103], v[150:151], v[102:103], v[178:179]
	s_add_u32 s98, s10, 0x30000
	s_addc_u32 s99, s11, 0
	global_store_dwordx4 v203, v[100:103], s[98:99]
	s_add_u32 s42, s10, 0xa0000
	s_addc_u32 s43, s11, 0
	global_load_dwordx4 v[176:179], v203, s[42:43] offset:16
	s_waitcnt vmcnt(24)
	v_pk_fma_f32 v[96:97], v[144:145], v[96:97], v[180:181]
	v_pk_fma_f32 v[98:99], v[146:147], v[98:99], v[182:183]
	s_add_u32 s98, s10, 0x30000
	s_addc_u32 s99, s11, 0
	global_store_dwordx4 v203, v[96:99], s[98:99] offset:16
	s_add_u32 s42, s10, 0xa0200
	s_addc_u32 s43, s11, 0
	global_load_dwordx4 v[180:183], v203, s[42:43]
	s_waitcnt vmcnt(24)
	v_pk_fma_f32 v[68:69], v[156:157], v[68:69], v[206:207]
	v_pk_fma_f32 v[70:71], v[158:159], v[70:71], v[208:209]
	s_add_u32 s98, s10, 0x30200
	s_addc_u32 s99, s11, 0
	global_store_dwordx4 v203, v[68:71], s[98:99]
	s_add_u32 s42, s10, 0xa0200
	s_addc_u32 s43, s11, 0
	global_load_dwordx4 v[206:209], v203, s[42:43] offset:16
	s_waitcnt vmcnt(24)
	v_pk_fma_f32 v[64:65], v[152:153], v[64:65], v[210:211]
	v_pk_fma_f32 v[66:67], v[154:155], v[66:67], v[212:213]
	s_add_u32 s98, s10, 0x30200
	s_addc_u32 s99, s11, 0
	global_store_dwordx4 v203, v[64:67], s[98:99] offset:16
	s_add_u32 s42, s10, 0xb0000
	s_addc_u32 s43, s11, 0
	global_load_dwordx4 v[210:213], v203, s[42:43]
	s_waitcnt vmcnt(24)
	v_pk_fma_f32 v[60:61], v[148:149], v[60:61], v[236:237]
	v_pk_fma_f32 v[62:63], v[150:151], v[62:63], v[238:239]
	s_add_u32 s98, s10, 0x80000
	s_addc_u32 s99, s11, 0
	global_store_dwordx4 v203, v[60:63], s[98:99]
	s_add_u32 s42, s10, 0xb0000
	s_addc_u32 s43, s11, 0
	global_load_dwordx4 v[236:239], v203, s[42:43] offset:16
	s_waitcnt vmcnt(24)
	v_pk_fma_f32 v[56:57], v[144:145], v[56:57], v[128:129]
	v_pk_fma_f32 v[58:59], v[146:147], v[58:59], v[130:131]
	s_add_u32 s98, s10, 0x80000
	s_addc_u32 s99, s11, 0
	global_store_dwordx4 v203, v[56:59], s[98:99] offset:16
	s_add_u32 s42, s10, 0xb0200
	s_addc_u32 s43, s11, 0
	global_load_dwordx4 v[128:131], v203, s[42:43]
	s_waitcnt vmcnt(24)
	v_pk_fma_f32 v[28:29], v[156:157], v[28:29], v[132:133]
	v_pk_fma_f32 v[30:31], v[158:159], v[30:31], v[134:135]
	s_add_u32 s98, s10, 0x80200
	s_addc_u32 s99, s11, 0
	global_store_dwordx4 v203, v[28:31], s[98:99]
	s_add_u32 s42, s10, 0xb0200
	s_addc_u32 s43, s11, 0
	global_load_dwordx4 v[132:135], v203, s[42:43] offset:16
	s_waitcnt vmcnt(24)
	v_pk_fma_f32 v[24:25], v[152:153], v[24:25], v[136:137]
	v_pk_fma_f32 v[26:27], v[154:155], v[26:27], v[138:139]
	s_add_u32 s98, s10, 0x80200
	s_addc_u32 s99, s11, 0
	global_store_dwordx4 v203, v[24:27], s[98:99] offset:16
	s_waitcnt vmcnt(23)
	v_pk_fma_f32 v[52:53], v[148:149], v[52:53], v[140:141]
	v_pk_fma_f32 v[54:55], v[150:151], v[54:55], v[142:143]
	s_add_u32 s42, s10, 0x90000
	s_addc_u32 s43, s11, 0
	global_store_dwordx4 v203, v[52:55], s[42:43]
	s_waitcnt vmcnt(22)
	v_pk_fma_f32 v[48:49], v[144:145], v[48:49], v[160:161]
	v_pk_fma_f32 v[50:51], v[146:147], v[50:51], v[162:163]
	s_add_u32 s98, s10, 0x90000
	s_addc_u32 s99, s11, 0
	global_store_dwordx4 v203, v[48:51], s[98:99] offset:16
	s_waitcnt vmcnt(21)
	v_pk_fma_f32 v[20:21], v[156:157], v[20:21], v[164:165]
	v_pk_fma_f32 v[22:23], v[158:159], v[22:23], v[166:167]
	s_add_u32 s42, s10, 0x90200
	s_addc_u32 s43, s11, 0
	global_store_dwordx4 v203, v[20:23], s[42:43]
	s_waitcnt vmcnt(20)
	v_pk_fma_f32 v[16:17], v[152:153], v[16:17], v[168:169]
	v_pk_fma_f32 v[18:19], v[154:155], v[18:19], v[170:171]
	s_add_u32 s98, s10, 0x90200
	s_addc_u32 s99, s11, 0
	global_store_dwordx4 v203, v[16:19], s[98:99] offset:16
	s_waitcnt vmcnt(19)
	v_pk_fma_f32 v[44:45], v[148:149], v[44:45], v[172:173]
	v_pk_fma_f32 v[46:47], v[150:151], v[46:47], v[174:175]
	s_add_u32 s42, s10, 0xa0000
	s_addc_u32 s43, s11, 0
	global_store_dwordx4 v203, v[44:47], s[42:43]
	s_waitcnt vmcnt(18)
	v_pk_fma_f32 v[40:41], v[144:145], v[40:41], v[176:177]
	v_pk_fma_f32 v[42:43], v[146:147], v[42:43], v[178:179]
	s_add_u32 s98, s10, 0xa0000
	s_addc_u32 s99, s11, 0
	global_store_dwordx4 v203, v[40:43], s[98:99] offset:16
	s_waitcnt vmcnt(17)
	v_pk_fma_f32 v[12:13], v[156:157], v[12:13], v[180:181]
	v_pk_fma_f32 v[14:15], v[158:159], v[14:15], v[182:183]
	s_add_u32 s42, s10, 0xa0200
	s_addc_u32 s43, s11, 0
	global_store_dwordx4 v203, v[12:15], s[42:43]
	s_waitcnt vmcnt(16)
	v_pk_fma_f32 v[8:9], v[152:153], v[8:9], v[206:207]
	v_pk_fma_f32 v[10:11], v[154:155], v[10:11], v[208:209]
	s_add_u32 s98, s10, 0xa0200
	s_addc_u32 s99, s11, 0
	global_store_dwordx4 v203, v[8:11], s[98:99] offset:16
	s_waitcnt vmcnt(15)
	v_pk_fma_f32 v[36:37], v[148:149], v[36:37], v[210:211]
	v_pk_fma_f32 v[38:39], v[150:151], v[38:39], v[212:213]
	s_add_u32 s42, s10, 0xb0000
	s_addc_u32 s43, s11, 0
	global_store_dwordx4 v203, v[36:39], s[42:43]
	s_waitcnt vmcnt(14)
	v_pk_fma_f32 v[32:33], v[144:145], v[32:33], v[236:237]
	v_pk_fma_f32 v[34:35], v[146:147], v[34:35], v[238:239]
	s_add_u32 s98, s10, 0xb0000
	s_addc_u32 s99, s11, 0
	global_store_dwordx4 v203, v[32:35], s[98:99] offset:16
	s_waitcnt vmcnt(13)
	v_pk_fma_f32 v[4:5], v[156:157], v[4:5], v[128:129]
	v_pk_fma_f32 v[6:7], v[158:159], v[6:7], v[130:131]
	s_add_u32 s42, s10, 0xb0200
	s_addc_u32 s43, s11, 0
	global_store_dwordx4 v203, v[4:7], s[42:43]
	s_waitcnt vmcnt(12)
	v_pk_fma_f32 v[0:1], v[152:153], v[0:1], v[132:133]
	v_pk_fma_f32 v[2:3], v[154:155], v[2:3], v[134:135]
	s_add_u32 s98, s10, 0xb0200
	s_addc_u32 s99, s11, 0
	global_store_dwordx4 v203, v[0:3], s[98:99] offset:16
	s_branch .Lfq_predone
.Lfq_np2:
	s_add_u32 s42, s62, 0x0
	s_addc_u32 s43, s63, 0
	global_load_dwordx4 v[128:131], v205, s[42:43] sc0 sc1
	s_add_u32 s98, s62, 0x1000
	s_addc_u32 s99, s63, 0
	global_load_dwordx4 v[132:135], v205, s[98:99] sc0 sc1
	s_add_u32 s42, s62, 0x400
	s_addc_u32 s43, s63, 0
	global_load_dwordx4 v[136:139], v205, s[42:43] sc0 sc1
	s_add_u32 s98, s62, 0x1400
	s_addc_u32 s99, s63, 0
	global_load_dwordx4 v[140:143], v205, s[98:99] sc0 sc1
	s_add_u32 s42, s62, 0x800
	s_addc_u32 s43, s63, 0
	global_load_dwordx4 v[160:163], v205, s[42:43] sc0 sc1
	s_add_u32 s98, s62, 0x1800
	s_addc_u32 s99, s63, 0
	global_load_dwordx4 v[164:167], v205, s[98:99] sc0 sc1
	s_add_u32 s42, s62, 0xc00
	s_addc_u32 s43, s63, 0
	global_load_dwordx4 v[168:171], v205, s[42:43] sc0 sc1
	s_add_u32 s98, s62, 0x1c00
	s_addc_u32 s99, s63, 0
	global_load_dwordx4 v[172:175], v205, s[98:99] sc0 sc1
	s_add_u32 s42, s62, 0x2000
	s_addc_u32 s43, s63, 0
	global_load_dwordx4 v[176:179], v205, s[42:43] sc0 sc1
	s_add_u32 s98, s62, 0x3000
	s_addc_u32 s99, s63, 0
	global_load_dwordx4 v[180:183], v205, s[98:99] sc0 sc1
	s_add_u32 s42, s62, 0x2400
	s_addc_u32 s43, s63, 0
	global_load_dwordx4 v[206:209], v205, s[42:43] sc0 sc1
	s_add_u32 s98, s62, 0x3400
	s_addc_u32 s99, s63, 0
	global_load_dwordx4 v[210:213], v205, s[98:99] sc0 sc1
	s_add_u32 s42, s62, 0x2800
	s_addc_u32 s43, s63, 0
	global_load_dwordx4 v[236:239], v205, s[42:43] sc0 sc1
	s_waitcnt vmcnt(12)
	v_lshlrev_b32_e32 v240, 16, v128
	v_and_b32_e32 v241, 0xffff0000, v128
	v_pk_add_f32 v[124:125], v[124:125], v[240:241]
	v_lshlrev_b32_e32 v240, 16, v129
	v_and_b32_e32 v241, 0xffff0000, v129
	v_pk_add_f32 v[126:127], v[126:127], v[240:241]
	v_lshlrev_b32_e32 v240, 16, v130
	v_and_b32_e32 v241, 0xffff0000, v130
	v_pk_add_f32 v[120:121], v[120:121], v[240:241]
	v_lshlrev_b32_e32 v240, 16, v131
	v_and_b32_e32 v241, 0xffff0000, v131
	v_pk_add_f32 v[122:123], v[122:123], v[240:241]
	s_add_u32 s98, s62, 0x3800
	s_addc_u32 s99, s63, 0
	global_load_dwordx4 v[128:131], v205, s[98:99] sc0 sc1
	s_waitcnt vmcnt(12)
	v_lshlrev_b32_e32 v240, 16, v132
	v_and_b32_e32 v241, 0xffff0000, v132
	v_pk_add_f32 v[92:93], v[92:93], v[240:241]
	v_lshlrev_b32_e32 v240, 16, v133
	v_and_b32_e32 v241, 0xffff0000, v133
	v_pk_add_f32 v[94:95], v[94:95], v[240:241]
	v_lshlrev_b32_e32 v240, 16, v134
	v_and_b32_e32 v241, 0xffff0000, v134
	v_pk_add_f32 v[88:89], v[88:89], v[240:241]
	v_lshlrev_b32_e32 v240, 16, v135
	v_and_b32_e32 v241, 0xffff0000, v135
	v_pk_add_f32 v[90:91], v[90:91], v[240:241]
	s_add_u32 s42, s62, 0x2c00
	s_addc_u32 s43, s63, 0
	global_load_dwordx4 v[132:135], v205, s[42:43] sc0 sc1
	s_waitcnt vmcnt(12)
	v_lshlrev_b32_e32 v240, 16, v136
	v_and_b32_e32 v241, 0xffff0000, v136
	v_pk_add_f32 v[116:117], v[116:117], v[240:241]
	v_lshlrev_b32_e32 v240, 16, v137
	v_and_b32_e32 v241, 0xffff0000, v137
	v_pk_add_f32 v[118:119], v[118:119], v[240:241]
	v_lshlrev_b32_e32 v240, 16, v138
	v_and_b32_e32 v241, 0xffff0000, v138
	v_pk_add_f32 v[112:113], v[112:113], v[240:241]
	v_lshlrev_b32_e32 v240, 16, v139
	v_and_b32_e32 v241, 0xffff0000, v139
	v_pk_add_f32 v[114:115], v[114:115], v[240:241]
	s_add_u32 s98, s62, 0x3c00
	s_addc_u32 s99, s63, 0
	global_load_dwordx4 v[136:139], v205, s[98:99] sc0 sc1
	s_waitcnt vmcnt(12)
	v_lshlrev_b32_e32 v240, 16, v140
	v_and_b32_e32 v241, 0xffff0000, v140
	v_pk_add_f32 v[84:85], v[84:85], v[240:241]
	v_lshlrev_b32_e32 v240, 16, v141
	v_and_b32_e32 v241, 0xffff0000, v141
	v_pk_add_f32 v[86:87], v[86:87], v[240:241]
	v_lshlrev_b32_e32 v240, 16, v142
	v_and_b32_e32 v241, 0xffff0000, v142
	v_pk_add_f32 v[80:81], v[80:81], v[240:241]
	v_lshlrev_b32_e32 v240, 16, v143
	v_and_b32_e32 v241, 0xffff0000, v143
	v_pk_add_f32 v[82:83], v[82:83], v[240:241]
	s_add_u32 s42, s62, 0x20000
	s_addc_u32 s43, s63, 0
	global_load_dwordx4 v[140:143], v205, s[42:43] sc0 sc1
	s_waitcnt vmcnt(12)
	v_lshlrev_b32_e32 v240, 16, v160
	v_and_b32_e32 v241, 0xffff0000, v160
	v_pk_add_f32 v[108:109], v[108:109], v[240:241]
	v_lshlrev_b32_e32 v240, 16, v161
	v_and_b32_e32 v241, 0xffff0000, v161
	v_pk_add_f32 v[110:111], v[110:111], v[240:241]
	v_lshlrev_b32_e32 v240, 16, v162
	v_and_b32_e32 v241, 0xffff0000, v162
	v_pk_add_f32 v[104:105], v[104:105], v[240:241]
	v_lshlrev_b32_e32 v240, 16, v163
	v_and_b32_e32 v241, 0xffff0000, v163
	v_pk_add_f32 v[106:107], v[106:107], v[240:241]
	s_add_u32 s98, s62, 0x21000
	s_addc_u32 s99, s63, 0
	global_load_dwordx4 v[160:163], v205, s[98:99] sc0 sc1
	s_waitcnt vmcnt(12)
	v_lshlrev_b32_e32 v240, 16, v164
	v_and_b32_e32 v241, 0xffff0000, v164
	v_pk_add_f32 v[76:77], v[76:77], v[240:241]
	v_lshlrev_b32_e32 v240, 16, v165
	v_and_b32_e32 v241, 0xffff0000, v165
	v_pk_add_f32 v[78:79], v[78:79], v[240:241]
	v_lshlrev_b32_e32 v240, 16, v166
	v_and_b32_e32 v241, 0xffff0000, v166
	v_pk_add_f32 v[72:73], v[72:73], v[240:241]
	v_lshlrev_b32_e32 v240, 16, v167
	v_and_b32_e32 v241, 0xffff0000, v167
	v_pk_add_f32 v[74:75], v[74:75], v[240:241]
	s_add_u32 s42, s62, 0x20400
	s_addc_u32 s43, s63, 0
	global_load_dwordx4 v[164:167], v205, s[42:43] sc0 sc1
	s_waitcnt vmcnt(12)
	v_lshlrev_b32_e32 v240, 16, v168
	v_and_b32_e32 v241, 0xffff0000, v168
	v_pk_add_f32 v[100:101], v[100:101], v[240:241]
	v_lshlrev_b32_e32 v240, 16, v169
	v_and_b32_e32 v241, 0xffff0000, v169
	v_pk_add_f32 v[102:103], v[102:103], v[240:241]
	v_lshlrev_b32_e32 v240, 16, v170
	v_and_b32_e32 v241, 0xffff0000, v170
	v_pk_add_f32 v[96:97], v[96:97], v[240:241]
	v_lshlrev_b32_e32 v240, 16, v171
	v_and_b32_e32 v241, 0xffff0000, v171
	v_pk_add_f32 v[98:99], v[98:99], v[240:241]
	s_add_u32 s98, s62, 0x21400
	s_addc_u32 s99, s63, 0
	global_load_dwordx4 v[168:171], v205, s[98:99] sc0 sc1
	s_waitcnt vmcnt(12)
	v_lshlrev_b32_e32 v240, 16, v172
	v_and_b32_e32 v241, 0xffff0000, v172
	v_pk_add_f32 v[68:69], v[68:69], v[240:241]
	v_lshlrev_b32_e32 v240, 16, v173
	v_and_b32_e32 v241, 0xffff0000, v173
	v_pk_add_f32 v[70:71], v[70:71], v[240:241]
	v_lshlrev_b32_e32 v240, 16, v174
	v_and_b32_e32 v241, 0xffff0000, v174
	v_pk_add_f32 v[64:65], v[64:65], v[240:241]
	v_lshlrev_b32_e32 v240, 16, v175
	v_and_b32_e32 v241, 0xffff0000, v175
	v_pk_add_f32 v[66:67], v[66:67], v[240:241]
	s_add_u32 s42, s62, 0x20800
	s_addc_u32 s43, s63, 0
	global_load_dwordx4 v[172:175], v205, s[42:43] sc0 sc1
	s_waitcnt vmcnt(12)
	v_lshlrev_b32_e32 v240, 16, v176
	v_and_b32_e32 v241, 0xffff0000, v176
	v_pk_add_f32 v[60:61], v[60:61], v[240:241]
	v_lshlrev_b32_e32 v240, 16, v177
	v_and_b32_e32 v241, 0xffff0000, v177
	v_pk_add_f32 v[62:63], v[62:63], v[240:241]
	v_lshlrev_b32_e32 v240, 16, v178
	v_and_b32_e32 v241, 0xffff0000, v178
	v_pk_add_f32 v[56:57], v[56:57], v[240:241]
	v_lshlrev_b32_e32 v240, 16, v179
	v_and_b32_e32 v241, 0xffff0000, v179
	v_pk_add_f32 v[58:59], v[58:59], v[240:241]
	s_add_u32 s98, s62, 0x21800
	s_addc_u32 s99, s63, 0
	global_load_dwordx4 v[176:179], v205, s[98:99] sc0 sc1
	s_waitcnt vmcnt(12)
	v_lshlrev_b32_e32 v240, 16, v180
	v_and_b32_e32 v241, 0xffff0000, v180
	v_pk_add_f32 v[28:29], v[28:29], v[240:241]
	v_lshlrev_b32_e32 v240, 16, v181
	v_and_b32_e32 v241, 0xffff0000, v181
	v_pk_add_f32 v[30:31], v[30:31], v[240:241]
	v_lshlrev_b32_e32 v240, 16, v182
	v_and_b32_e32 v241, 0xffff0000, v182
	v_pk_add_f32 v[24:25], v[24:25], v[240:241]
	v_lshlrev_b32_e32 v240, 16, v183
	v_and_b32_e32 v241, 0xffff0000, v183
	v_pk_add_f32 v[26:27], v[26:27], v[240:241]
	s_add_u32 s42, s62, 0x20c00
	s_addc_u32 s43, s63, 0
	global_load_dwordx4 v[180:183], v205, s[42:43] sc0 sc1
	s_waitcnt vmcnt(12)
	v_lshlrev_b32_e32 v240, 16, v206
	v_and_b32_e32 v241, 0xffff0000, v206
	v_pk_add_f32 v[52:53], v[52:53], v[240:241]
	v_lshlrev_b32_e32 v240, 16, v207
	v_and_b32_e32 v241, 0xffff0000, v207
	v_pk_add_f32 v[54:55], v[54:55], v[240:241]
	v_lshlrev_b32_e32 v240, 16, v208
	v_and_b32_e32 v241, 0xffff0000, v208
	v_pk_add_f32 v[48:49], v[48:49], v[240:241]
	v_lshlrev_b32_e32 v240, 16, v209
	v_and_b32_e32 v241, 0xffff0000, v209
	v_pk_add_f32 v[50:51], v[50:51], v[240:241]
	s_add_u32 s98, s62, 0x21c00
	s_addc_u32 s99, s63, 0
	global_load_dwordx4 v[206:209], v205, s[98:99] sc0 sc1
	s_waitcnt vmcnt(12)
	v_lshlrev_b32_e32 v240, 16, v210
	v_and_b32_e32 v241, 0xffff0000, v210
	v_pk_add_f32 v[20:21], v[20:21], v[240:241]
	v_lshlrev_b32_e32 v240, 16, v211
	v_and_b32_e32 v241, 0xffff0000, v211
	v_pk_add_f32 v[22:23], v[22:23], v[240:241]
	v_lshlrev_b32_e32 v240, 16, v212
	v_and_b32_e32 v241, 0xffff0000, v212
	v_pk_add_f32 v[16:17], v[16:17], v[240:241]
	v_lshlrev_b32_e32 v240, 16, v213
	v_and_b32_e32 v241, 0xffff0000, v213
	v_pk_add_f32 v[18:19], v[18:19], v[240:241]
	s_add_u32 s42, s62, 0x22000
	s_addc_u32 s43, s63, 0
	global_load_dwordx4 v[210:213], v205, s[42:43] sc0 sc1
	s_waitcnt vmcnt(12)
	v_lshlrev_b32_e32 v240, 16, v236
	v_and_b32_e32 v241, 0xffff0000, v236
	v_pk_add_f32 v[44:45], v[44:45], v[240:241]
	v_lshlrev_b32_e32 v240, 16, v237
	v_and_b32_e32 v241, 0xffff0000, v237
	v_pk_add_f32 v[46:47], v[46:47], v[240:241]
	v_lshlrev_b32_e32 v240, 16, v238
	v_and_b32_e32 v241, 0xffff0000, v238
	v_pk_add_f32 v[40:41], v[40:41], v[240:241]
	v_lshlrev_b32_e32 v240, 16, v239
	v_and_b32_e32 v241, 0xffff0000, v239
	v_pk_add_f32 v[42:43], v[42:43], v[240:241]
	s_add_u32 s98, s62, 0x23000
	s_addc_u32 s99, s63, 0
	global_load_dwordx4 v[236:239], v205, s[98:99] sc0 sc1
	s_waitcnt vmcnt(12)
	v_lshlrev_b32_e32 v240, 16, v128
	v_and_b32_e32 v241, 0xffff0000, v128
	v_pk_add_f32 v[12:13], v[12:13], v[240:241]
	v_lshlrev_b32_e32 v240, 16, v129
	v_and_b32_e32 v241, 0xffff0000, v129
	v_pk_add_f32 v[14:15], v[14:15], v[240:241]
	v_lshlrev_b32_e32 v240, 16, v130
	v_and_b32_e32 v241, 0xffff0000, v130
	v_pk_add_f32 v[8:9], v[8:9], v[240:241]
	v_lshlrev_b32_e32 v240, 16, v131
	v_and_b32_e32 v241, 0xffff0000, v131
	v_pk_add_f32 v[10:11], v[10:11], v[240:241]
	s_add_u32 s42, s62, 0x22400
	s_addc_u32 s43, s63, 0
	global_load_dwordx4 v[128:131], v205, s[42:43] sc0 sc1
	s_waitcnt vmcnt(12)
	v_lshlrev_b32_e32 v240, 16, v132
	v_and_b32_e32 v241, 0xffff0000, v132
	v_pk_add_f32 v[36:37], v[36:37], v[240:241]
	v_lshlrev_b32_e32 v240, 16, v133
	v_and_b32_e32 v241, 0xffff0000, v133
	v_pk_add_f32 v[38:39], v[38:39], v[240:241]
	v_lshlrev_b32_e32 v240, 16, v134
	v_and_b32_e32 v241, 0xffff0000, v134
	v_pk_add_f32 v[32:33], v[32:33], v[240:241]
	v_lshlrev_b32_e32 v240, 16, v135
	v_and_b32_e32 v241, 0xffff0000, v135
	v_pk_add_f32 v[34:35], v[34:35], v[240:241]
	s_add_u32 s98, s62, 0x23400
	s_addc_u32 s99, s63, 0
	global_load_dwordx4 v[132:135], v205, s[98:99] sc0 sc1
	s_waitcnt vmcnt(12)
	v_lshlrev_b32_e32 v240, 16, v136
	v_and_b32_e32 v241, 0xffff0000, v136
	v_pk_add_f32 v[4:5], v[4:5], v[240:241]
	v_lshlrev_b32_e32 v240, 16, v137
	v_and_b32_e32 v241, 0xffff0000, v137
	v_pk_add_f32 v[6:7], v[6:7], v[240:241]
	v_lshlrev_b32_e32 v240, 16, v138
	v_and_b32_e32 v241, 0xffff0000, v138
	v_pk_add_f32 v[0:1], v[0:1], v[240:241]
	v_lshlrev_b32_e32 v240, 16, v139
	v_and_b32_e32 v241, 0xffff0000, v139
	v_pk_add_f32 v[2:3], v[2:3], v[240:241]
	s_add_u32 s42, s62, 0x22800
	s_addc_u32 s43, s63, 0
	global_load_dwordx4 v[136:139], v205, s[42:43] sc0 sc1
	s_waitcnt vmcnt(12)
	v_lshlrev_b32_e32 v240, 16, v140
	v_and_b32_e32 v241, 0xffff0000, v140
	v_pk_add_f32 v[124:125], v[124:125], v[240:241]
	v_lshlrev_b32_e32 v240, 16, v141
	v_and_b32_e32 v241, 0xffff0000, v141
	v_pk_add_f32 v[126:127], v[126:127], v[240:241]
	v_lshlrev_b32_e32 v240, 16, v142
	v_and_b32_e32 v241, 0xffff0000, v142
	v_pk_add_f32 v[120:121], v[120:121], v[240:241]
	v_lshlrev_b32_e32 v240, 16, v143
	v_and_b32_e32 v241, 0xffff0000, v143
	v_pk_add_f32 v[122:123], v[122:123], v[240:241]
	s_add_u32 s98, s62, 0x23800
	s_addc_u32 s99, s63, 0
	global_load_dwordx4 v[140:143], v205, s[98:99] sc0 sc1
	s_waitcnt vmcnt(12)
	v_lshlrev_b32_e32 v240, 16, v160
	v_and_b32_e32 v241, 0xffff0000, v160
	v_pk_add_f32 v[92:93], v[92:93], v[240:241]
	v_lshlrev_b32_e32 v240, 16, v161
	v_and_b32_e32 v241, 0xffff0000, v161
	v_pk_add_f32 v[94:95], v[94:95], v[240:241]
	v_lshlrev_b32_e32 v240, 16, v162
	v_and_b32_e32 v241, 0xffff0000, v162
	v_pk_add_f32 v[88:89], v[88:89], v[240:241]
	v_lshlrev_b32_e32 v240, 16, v163
	v_and_b32_e32 v241, 0xffff0000, v163
	v_pk_add_f32 v[90:91], v[90:91], v[240:241]
	s_add_u32 s42, s62, 0x22c00
	s_addc_u32 s43, s63, 0
	global_load_dwordx4 v[160:163], v205, s[42:43] sc0 sc1
	s_waitcnt vmcnt(12)
	v_lshlrev_b32_e32 v240, 16, v164
	v_and_b32_e32 v241, 0xffff0000, v164
	v_pk_add_f32 v[116:117], v[116:117], v[240:241]
	v_lshlrev_b32_e32 v240, 16, v165
	v_and_b32_e32 v241, 0xffff0000, v165
	v_pk_add_f32 v[118:119], v[118:119], v[240:241]
	v_lshlrev_b32_e32 v240, 16, v166
	v_and_b32_e32 v241, 0xffff0000, v166
	v_pk_add_f32 v[112:113], v[112:113], v[240:241]
	v_lshlrev_b32_e32 v240, 16, v167
	v_and_b32_e32 v241, 0xffff0000, v167
	v_pk_add_f32 v[114:115], v[114:115], v[240:241]
	s_add_u32 s98, s62, 0x23c00
	s_addc_u32 s99, s63, 0
	global_load_dwordx4 v[164:167], v205, s[98:99] sc0 sc1
	s_waitcnt vmcnt(12)
	v_lshlrev_b32_e32 v240, 16, v168
	v_and_b32_e32 v241, 0xffff0000, v168
	v_pk_add_f32 v[84:85], v[84:85], v[240:241]
	v_lshlrev_b32_e32 v240, 16, v169
	v_and_b32_e32 v241, 0xffff0000, v169
	v_pk_add_f32 v[86:87], v[86:87], v[240:241]
	v_lshlrev_b32_e32 v240, 16, v170
	v_and_b32_e32 v241, 0xffff0000, v170
	v_pk_add_f32 v[80:81], v[80:81], v[240:241]
	v_lshlrev_b32_e32 v240, 16, v171
	v_and_b32_e32 v241, 0xffff0000, v171
	v_pk_add_f32 v[82:83], v[82:83], v[240:241]
	s_add_u32 s42, s10, 0x0
	s_addc_u32 s43, s11, 0
	global_load_dwordx4 v[168:171], v203, s[42:43]
	s_waitcnt vmcnt(12)
	v_lshlrev_b32_e32 v240, 16, v172
	v_and_b32_e32 v241, 0xffff0000, v172
	v_pk_add_f32 v[108:109], v[108:109], v[240:241]
	v_lshlrev_b32_e32 v240, 16, v173
	v_and_b32_e32 v241, 0xffff0000, v173
	v_pk_add_f32 v[110:111], v[110:111], v[240:241]
	v_lshlrev_b32_e32 v240, 16, v174
	v_and_b32_e32 v241, 0xffff0000, v174
	v_pk_add_f32 v[104:105], v[104:105], v[240:241]
	v_lshlrev_b32_e32 v240, 16, v175
	v_and_b32_e32 v241, 0xffff0000, v175
	v_pk_add_f32 v[106:107], v[106:107], v[240:241]
	s_add_u32 s98, s10, 0x0
	s_addc_u32 s99, s11, 0
	global_load_dwordx4 v[172:175], v203, s[98:99] offset:16
	s_waitcnt vmcnt(12)
	v_lshlrev_b32_e32 v240, 16, v176
	v_and_b32_e32 v241, 0xffff0000, v176
	v_pk_add_f32 v[76:77], v[76:77], v[240:241]
	v_lshlrev_b32_e32 v240, 16, v177
	v_and_b32_e32 v241, 0xffff0000, v177
	v_pk_add_f32 v[78:79], v[78:79], v[240:241]
	v_lshlrev_b32_e32 v240, 16, v178
	v_and_b32_e32 v241, 0xffff0000, v178
	v_pk_add_f32 v[72:73], v[72:73], v[240:241]
	v_lshlrev_b32_e32 v240, 16, v179
	v_and_b32_e32 v241, 0xffff0000, v179
	v_pk_add_f32 v[74:75], v[74:75], v[240:241]
	s_add_u32 s42, s10, 0x200
	s_addc_u32 s43, s11, 0
	global_load_dwordx4 v[176:179], v203, s[42:43]
	s_waitcnt vmcnt(12)
	v_lshlrev_b32_e32 v240, 16, v180
	v_and_b32_e32 v241, 0xffff0000, v180
	v_pk_add_f32 v[100:101], v[100:101], v[240:241]
	v_lshlrev_b32_e32 v240, 16, v181
	v_and_b32_e32 v241, 0xffff0000, v181
	v_pk_add_f32 v[102:103], v[102:103], v[240:241]
	v_lshlrev_b32_e32 v240, 16, v182
	v_and_b32_e32 v241, 0xffff0000, v182
	v_pk_add_f32 v[96:97], v[96:97], v[240:241]
	v_lshlrev_b32_e32 v240, 16, v183
	v_and_b32_e32 v241, 0xffff0000, v183
	v_pk_add_f32 v[98:99], v[98:99], v[240:241]
	s_add_u32 s98, s10, 0x200
	s_addc_u32 s99, s11, 0
	global_load_dwordx4 v[180:183], v203, s[98:99] offset:16
	s_waitcnt vmcnt(12)
	v_lshlrev_b32_e32 v240, 16, v206
	v_and_b32_e32 v241, 0xffff0000, v206
	v_pk_add_f32 v[68:69], v[68:69], v[240:241]
	v_lshlrev_b32_e32 v240, 16, v207
	v_and_b32_e32 v241, 0xffff0000, v207
	v_pk_add_f32 v[70:71], v[70:71], v[240:241]
	v_lshlrev_b32_e32 v240, 16, v208
	v_and_b32_e32 v241, 0xffff0000, v208
	v_pk_add_f32 v[64:65], v[64:65], v[240:241]
	v_lshlrev_b32_e32 v240, 16, v209
	v_and_b32_e32 v241, 0xffff0000, v209
	v_pk_add_f32 v[66:67], v[66:67], v[240:241]
	s_add_u32 s42, s10, 0x10000
	s_addc_u32 s43, s11, 0
	global_load_dwordx4 v[206:209], v203, s[42:43]
	s_waitcnt vmcnt(12)
	v_lshlrev_b32_e32 v240, 16, v210
	v_and_b32_e32 v241, 0xffff0000, v210
	v_pk_add_f32 v[60:61], v[60:61], v[240:241]
	v_lshlrev_b32_e32 v240, 16, v211
	v_and_b32_e32 v241, 0xffff0000, v211
	v_pk_add_f32 v[62:63], v[62:63], v[240:241]
	v_lshlrev_b32_e32 v240, 16, v212
	v_and_b32_e32 v241, 0xffff0000, v212
	v_pk_add_f32 v[56:57], v[56:57], v[240:241]
	v_lshlrev_b32_e32 v240, 16, v213
	v_and_b32_e32 v241, 0xffff0000, v213
	v_pk_add_f32 v[58:59], v[58:59], v[240:241]
	s_add_u32 s98, s10, 0x10000
	s_addc_u32 s99, s11, 0
	global_load_dwordx4 v[210:213], v203, s[98:99] offset:16
	s_waitcnt vmcnt(12)
	v_lshlrev_b32_e32 v240, 16, v236
	v_and_b32_e32 v241, 0xffff0000, v236
	v_pk_add_f32 v[28:29], v[28:29], v[240:241]
	v_lshlrev_b32_e32 v240, 16, v237
	v_and_b32_e32 v241, 0xffff0000, v237
	v_pk_add_f32 v[30:31], v[30:31], v[240:241]
	v_lshlrev_b32_e32 v240, 16, v238
	v_and_b32_e32 v241, 0xffff0000, v238
	v_pk_add_f32 v[24:25], v[24:25], v[240:241]
	v_lshlrev_b32_e32 v240, 16, v239
	v_and_b32_e32 v241, 0xffff0000, v239
	v_pk_add_f32 v[26:27], v[26:27], v[240:241]
	s_add_u32 s42, s10, 0x10200
	s_addc_u32 s43, s11, 0
	global_load_dwordx4 v[236:239], v203, s[42:43]
	s_waitcnt vmcnt(12)
	v_lshlrev_b32_e32 v240, 16, v128
	v_and_b32_e32 v241, 0xffff0000, v128
	v_pk_add_f32 v[52:53], v[52:53], v[240:241]
	v_lshlrev_b32_e32 v240, 16, v129
	v_and_b32_e32 v241, 0xffff0000, v129
	v_pk_add_f32 v[54:55], v[54:55], v[240:241]
	v_lshlrev_b32_e32 v240, 16, v130
	v_and_b32_e32 v241, 0xffff0000, v130
	v_pk_add_f32 v[48:49], v[48:49], v[240:241]
	v_lshlrev_b32_e32 v240, 16, v131
	v_and_b32_e32 v241, 0xffff0000, v131
	v_pk_add_f32 v[50:51], v[50:51], v[240:241]
	s_add_u32 s98, s10, 0x10200
	s_addc_u32 s99, s11, 0
	global_load_dwordx4 v[128:131], v203, s[98:99] offset:16
	s_waitcnt vmcnt(12)
	v_lshlrev_b32_e32 v240, 16, v132
	v_and_b32_e32 v241, 0xffff0000, v132
	v_pk_add_f32 v[20:21], v[20:21], v[240:241]
	v_lshlrev_b32_e32 v240, 16, v133
	v_and_b32_e32 v241, 0xffff0000, v133
	v_pk_add_f32 v[22:23], v[22:23], v[240:241]
	v_lshlrev_b32_e32 v240, 16, v134
	v_and_b32_e32 v241, 0xffff0000, v134
	v_pk_add_f32 v[16:17], v[16:17], v[240:241]
	v_lshlrev_b32_e32 v240, 16, v135
	v_and_b32_e32 v241, 0xffff0000, v135
	v_pk_add_f32 v[18:19], v[18:19], v[240:241]
	s_add_u32 s42, s10, 0x20000
	s_addc_u32 s43, s11, 0
	global_load_dwordx4 v[132:135], v203, s[42:43]
	s_waitcnt vmcnt(12)
	v_lshlrev_b32_e32 v240, 16, v136
	v_and_b32_e32 v241, 0xffff0000, v136
	v_pk_add_f32 v[44:45], v[44:45], v[240:241]
	v_lshlrev_b32_e32 v240, 16, v137
	v_and_b32_e32 v241, 0xffff0000, v137
	v_pk_add_f32 v[46:47], v[46:47], v[240:241]
	v_lshlrev_b32_e32 v240, 16, v138
	v_and_b32_e32 v241, 0xffff0000, v138
	v_pk_add_f32 v[40:41], v[40:41], v[240:241]
	v_lshlrev_b32_e32 v240, 16, v139
	v_and_b32_e32 v241, 0xffff0000, v139
	v_pk_add_f32 v[42:43], v[42:43], v[240:241]
	s_add_u32 s98, s10, 0x20000
	s_addc_u32 s99, s11, 0
	global_load_dwordx4 v[136:139], v203, s[98:99] offset:16
	s_waitcnt vmcnt(12)
	v_lshlrev_b32_e32 v240, 16, v140
	v_and_b32_e32 v241, 0xffff0000, v140
	v_pk_add_f32 v[12:13], v[12:13], v[240:241]
	v_lshlrev_b32_e32 v240, 16, v141
	v_and_b32_e32 v241, 0xffff0000, v141
	v_pk_add_f32 v[14:15], v[14:15], v[240:241]
	v_lshlrev_b32_e32 v240, 16, v142
	v_and_b32_e32 v241, 0xffff0000, v142
	v_pk_add_f32 v[8:9], v[8:9], v[240:241]
	v_lshlrev_b32_e32 v240, 16, v143
	v_and_b32_e32 v241, 0xffff0000, v143
	v_pk_add_f32 v[10:11], v[10:11], v[240:241]
	s_add_u32 s42, s10, 0x20200
	s_addc_u32 s43, s11, 0
	global_load_dwordx4 v[140:143], v203, s[42:43]
	s_waitcnt vmcnt(12)
	v_lshlrev_b32_e32 v240, 16, v160
	v_and_b32_e32 v241, 0xffff0000, v160
	v_pk_add_f32 v[36:37], v[36:37], v[240:241]
	v_lshlrev_b32_e32 v240, 16, v161
	v_and_b32_e32 v241, 0xffff0000, v161
	v_pk_add_f32 v[38:39], v[38:39], v[240:241]
	v_lshlrev_b32_e32 v240, 16, v162
	v_and_b32_e32 v241, 0xffff0000, v162
	v_pk_add_f32 v[32:33], v[32:33], v[240:241]
	v_lshlrev_b32_e32 v240, 16, v163
	v_and_b32_e32 v241, 0xffff0000, v163
	v_pk_add_f32 v[34:35], v[34:35], v[240:241]
	s_add_u32 s98, s10, 0x20200
	s_addc_u32 s99, s11, 0
	global_load_dwordx4 v[160:163], v203, s[98:99] offset:16
	s_waitcnt vmcnt(12)
	v_lshlrev_b32_e32 v240, 16, v164
	v_and_b32_e32 v241, 0xffff0000, v164
	v_pk_add_f32 v[4:5], v[4:5], v[240:241]
	v_lshlrev_b32_e32 v240, 16, v165
	v_and_b32_e32 v241, 0xffff0000, v165
	v_pk_add_f32 v[6:7], v[6:7], v[240:241]
	v_lshlrev_b32_e32 v240, 16, v166
	v_and_b32_e32 v241, 0xffff0000, v166
	v_pk_add_f32 v[0:1], v[0:1], v[240:241]
	v_lshlrev_b32_e32 v240, 16, v167
	v_and_b32_e32 v241, 0xffff0000, v167
	v_pk_add_f32 v[2:3], v[2:3], v[240:241]
	s_add_u32 s42, s10, 0x30000
	s_addc_u32 s43, s11, 0
	global_load_dwordx4 v[164:167], v203, s[42:43]
	s_waitcnt vmcnt(12)
	v_pk_fma_f32 v[124:125], v[148:149], v[124:125], v[168:169]
	v_pk_fma_f32 v[126:127], v[150:151], v[126:127], v[170:171]
	s_add_u32 s98, s10, 0x0
	s_addc_u32 s99, s11, 0
	global_store_dwordx4 v203, v[124:127], s[98:99]
	s_add_u32 s42, s10, 0x30000
	s_addc_u32 s43, s11, 0
	global_load_dwordx4 v[168:171], v203, s[42:43] offset:16
	s_waitcnt vmcnt(13)
	v_pk_fma_f32 v[120:121], v[144:145], v[120:121], v[172:173]
	v_pk_fma_f32 v[122:123], v[146:147], v[122:123], v[174:175]
	s_add_u32 s98, s10, 0x0
	s_addc_u32 s99, s11, 0
	global_store_dwordx4 v203, v[120:123], s[98:99] offset:16
	s_add_u32 s42, s10, 0x30200
	s_addc_u32 s43, s11, 0
	global_load_dwordx4 v[172:175], v203, s[42:43]
	s_waitcnt vmcnt(14)
	v_pk_fma_f32 v[92:93], v[156:157], v[92:93], v[176:177]
	v_pk_fma_f32 v[94:95], v[158:159], v[94:95], v[178:179]
	s_add_u32 s98, s10, 0x200
	s_addc_u32 s99, s11, 0
	global_store_dwordx4 v203, v[92:95], s[98:99]
	s_add_u32 s42, s10, 0x30200
	s_addc_u32 s43, s11, 0
	global_load_dwordx4 v[176:179], v203, s[42:43] offset:16
	s_waitcnt vmcnt(15)
	v_pk_fma_f32 v[88:89], v[152:153], v[88:89], v[180:181]
	v_pk_fma_f32 v[90:91], v[154:155], v[90:91], v[182:183]
	s_add_u32 s98, s10, 0x200
	s_addc_u32 s99, s11, 0
	global_store_dwordx4 v203, v[88:91], s[98:99] offset:16
	s_add_u32 s42, s10, 0x80000
	s_addc_u32 s43, s11, 0
	global_load_dwordx4 v[180:183], v203, s[42:43]
	s_waitcnt vmcnt(16)
	v_pk_fma_f32 v[116:117], v[148:149], v[116:117], v[206:207]
	v_pk_fma_f32 v[118:119], v[150:151], v[118:119], v[208:209]
	s_add_u32 s98, s10, 0x10000
	s_addc_u32 s99, s11, 0
	global_store_dwordx4 v203, v[116:119], s[98:99]
	s_add_u32 s42, s10, 0x80000
	s_addc_u32 s43, s11, 0
	global_load_dwordx4 v[206:209], v203, s[42:43] offset:16
	s_waitcnt vmcnt(17)
	v_pk_fma_f32 v[112:113], v[144:145], v[112:113], v[210:211]
	v_pk_fma_f32 v[114:115], v[146:147], v[114:115], v[212:213]
	s_add_u32 s98, s10, 0x10000
	s_addc_u32 s99, s11, 0
	global_store_dwordx4 v203, v[112:115], s[98:99] offset:16
	s_add_u32 s42, s10, 0x80200
	s_addc_u32 s43, s11, 0
	global_load_dwordx4 v[210:213], v203, s[42:43]
	s_waitcnt vmcnt(18)
	v_pk_fma_f32 v[84:85], v[156:157], v[84:85], v[236:237]
	v_pk_fma_f32 v[86:87], v[158:159], v[86:87], v[238:239]
	s_add_u32 s98, s10, 0x10200
	s_addc_u32 s99, s11, 0
	global_store_dwordx4 v203, v[84:87], s[98:99]
	s_add_u32 s42, s10, 0x80200
	s_addc_u32 s43, s11, 0
	global_load_dwordx4 v[236:239], v203, s[42:43] offset:16
	s_waitcnt vmcnt(19)
	v_pk_fma_f32 v[80:81], v[152:153], v[80:81], v[128:129]
	v_pk_fma_f32 v[82:83], v[154:155], v[82:83], v[130:131]
	s_add_u32 s98, s10, 0x10200
	s_addc_u32 s99, s11, 0
	global_store_dwordx4 v203, v[80:83], s[98:99] offset:16
	s_add_u32 s42, s10, 0x90000
	s_addc_u32 s43, s11, 0
	global_load_dwordx4 v[128:131], v203, s[42:43]
	s_waitcnt vmcnt(20)
	v_pk_fma_f32 v[108:109], v[148:149], v[108:109], v[132:133]
	v_pk_fma_f32 v[110:111], v[150:151], v[110:111], v[134:135]
	s_add_u32 s98, s10, 0x20000
	s_addc_u32 s99, s11, 0
	global_store_dwordx4 v203, v[108:111], s[98:99]
	s_add_u32 s42, s10, 0x90000
	s_addc_u32 s43, s11, 0
	global_load_dwordx4 v[132:135], v203, s[42:43] offset:16
	s_waitcnt vmcnt(21)
	v_pk_fma_f32 v[104:105], v[144:145], v[104:105], v[136:137]
	v_pk_fma_f32 v[106:107], v[146:147], v[106:107], v[138:139]
	s_add_u32 s98, s10, 0x20000
	s_addc_u32 s99, s11, 0
	global_store_dwordx4 v203, v[104:107], s[98:99] offset:16
	s_add_u32 s42, s10, 0x90200
	s_addc_u32 s43, s11, 0
	global_load_dwordx4 v[136:139], v203, s[42:43]
	s_waitcnt vmcnt(22)
	v_pk_fma_f32 v[76:77], v[156:157], v[76:77], v[140:141]
	v_pk_fma_f32 v[78:79], v[158:159], v[78:79], v[142:143]
	s_add_u32 s98, s10, 0x20200
	s_addc_u32 s99, s11, 0
	global_store_dwordx4 v203, v[76:79], s[98:99]
	s_add_u32 s42, s10, 0x90200
	s_addc_u32 s43, s11, 0
	global_load_dwordx4 v[140:143], v203, s[42:43] offset:16
	s_waitcnt vmcnt(23)
	v_pk_fma_f32 v[72:73], v[152:153], v[72:73], v[160:161]
	v_pk_fma_f32 v[74:75], v[154:155], v[74:75], v[162:163]
	s_add_u32 s98, s10, 0x20200
	s_addc_u32 s99, s11, 0
	global_store_dwordx4 v203, v[72:75], s[98:99] offset:16
	s_add_u32 s42, s10, 0xa0000
	s_addc_u32 s43, s11, 0
	global_load_dwordx4 v[160:163], v203, s[42:43]
	s_waitcnt vmcnt(24)
	v_pk_fma_f32 v[100:101], v[148:149], v[100:101], v[164:165]
	v_pk_fma_f32 v[102:103], v[150:151], v[102:103], v[166:167]
	s_add_u32 s98, s10, 0x30000
	s_addc_u32 s99, s11, 0
	global_store_dwordx4 v203, v[100:103], s[98:99]
	s_add_u32 s42, s10, 0xa0000
	s_addc_u32 s43, s11, 0
	global_load_dwordx4 v[164:167], v203, s[42:43] offset:16
	s_waitcnt vmcnt(24)
	v_pk_fma_f32 v[96:97], v[144:145], v[96:97], v[168:169]
	v_pk_fma_f32 v[98:99], v[146:147], v[98:99], v[170:171]
	s_add_u32 s98, s10, 0x30000
	s_addc_u32 s99, s11, 0
	global_store_dwordx4 v203, v[96:99], s[98:99] offset:16
	s_add_u32 s42, s10, 0xa0200
	s_addc_u32 s43, s11, 0
	global_load_dwordx4 v[168:171], v203, s[42:43]
	s_waitcnt vmcnt(24)
	v_pk_fma_f32 v[68:69], v[156:157], v[68:69], v[172:173]
	v_pk_fma_f32 v[70:71], v[158:159], v[70:71], v[174:175]
	s_add_u32 s98, s10, 0x30200
	s_addc_u32 s99, s11, 0
	global_store_dwordx4 v203, v[68:71], s[98:99]
	s_add_u32 s42, s10, 0xa0200
	s_addc_u32 s43, s11, 0
	global_load_dwordx4 v[172:175], v203, s[42:43] offset:16
	s_waitcnt vmcnt(24)
	v_pk_fma_f32 v[64:65], v[152:153], v[64:65], v[176:177]
	v_pk_fma_f32 v[66:67], v[154:155], v[66:67], v[178:179]
	s_add_u32 s98, s10, 0x30200
	s_addc_u32 s99, s11, 0
	global_store_dwordx4 v203, v[64:67], s[98:99] offset:16
	s_add_u32 s42, s10, 0xb0000
	s_addc_u32 s43, s11, 0
	global_load_dwordx4 v[176:179], v203, s[42:43]
	s_waitcnt vmcnt(24)
	v_pk_fma_f32 v[60:61], v[148:149], v[60:61], v[180:181]
	v_pk_fma_f32 v[62:63], v[150:151], v[62:63], v[182:183]
	s_add_u32 s98, s10, 0x80000
	s_addc_u32 s99, s11, 0
	global_store_dwordx4 v203, v[60:63], s[98:99]
	s_add_u32 s42, s10, 0xb0000
	s_addc_u32 s43, s11, 0
	global_load_dwordx4 v[180:183], v203, s[42:43] offset:16
	s_waitcnt vmcnt(24)
	v_pk_fma_f32 v[56:57], v[144:145], v[56:57], v[206:207]
	v_pk_fma_f32 v[58:59], v[146:147], v[58:59], v[208:209]
	s_add_u32 s98, s10, 0x80000
	s_addc_u32 s99, s11, 0
	global_store_dwordx4 v203, v[56:59], s[98:99] offset:16
	s_add_u32 s42, s10, 0xb0200
	s_addc_u32 s43, s11, 0
	global_load_dwordx4 v[206:209], v203, s[42:43]
	s_waitcnt vmcnt(24)
	v_pk_fma_f32 v[28:29], v[156:157], v[28:29], v[210:211]
	v_pk_fma_f32 v[30:31], v[158:159], v[30:31], v[212:213]
	s_add_u32 s98, s10, 0x80200
	s_addc_u32 s99, s11, 0
	global_store_dwordx4 v203, v[28:31], s[98:99]
	s_add_u32 s42, s10, 0xb0200
	s_addc_u32 s43, s11, 0
	global_load_dwordx4 v[210:213], v203, s[42:43] offset:16
	s_waitcnt vmcnt(24)
	v_pk_fma_f32 v[24:25], v[152:153], v[24:25], v[236:237]
	v_pk_fma_f32 v[26:27], v[154:155], v[26:27], v[238:239]
	s_add_u32 s98, s10, 0x80200
	s_addc_u32 s99, s11, 0
	global_store_dwordx4 v203, v[24:27], s[98:99] offset:16
	s_waitcnt vmcnt(23)
	v_pk_fma_f32 v[52:53], v[148:149], v[52:53], v[128:129]
	v_pk_fma_f32 v[54:55], v[150:151], v[54:55], v[130:131]
	s_add_u32 s42, s10, 0x90000
	s_addc_u32 s43, s11, 0
	global_store_dwordx4 v203, v[52:55], s[42:43]
	s_waitcnt vmcnt(22)
	v_pk_fma_f32 v[48:49], v[144:145], v[48:49], v[132:133]
	v_pk_fma_f32 v[50:51], v[146:147], v[50:51], v[134:135]
	s_add_u32 s98, s10, 0x90000
	s_addc_u32 s99, s11, 0
	global_store_dwordx4 v203, v[48:51], s[98:99] offset:16
	s_waitcnt vmcnt(21)
	v_pk_fma_f32 v[20:21], v[156:157], v[20:21], v[136:137]
	v_pk_fma_f32 v[22:23], v[158:159], v[22:23], v[138:139]
	s_add_u32 s42, s10, 0x90200
	s_addc_u32 s43, s11, 0
	global_store_dwordx4 v203, v[20:23], s[42:43]
	s_waitcnt vmcnt(20)
	v_pk_fma_f32 v[16:17], v[152:153], v[16:17], v[140:141]
	v_pk_fma_f32 v[18:19], v[154:155], v[18:19], v[142:143]
	s_add_u32 s98, s10, 0x90200
	s_addc_u32 s99, s11, 0
	global_store_dwordx4 v203, v[16:19], s[98:99] offset:16
	s_waitcnt vmcnt(19)
	v_pk_fma_f32 v[44:45], v[148:149], v[44:45], v[160:161]
	v_pk_fma_f32 v[46:47], v[150:151], v[46:47], v[162:163]
	s_add_u32 s42, s10, 0xa0000
	s_addc_u32 s43, s11, 0
	global_store_dwordx4 v203, v[44:47], s[42:43]
	s_waitcnt vmcnt(18)
	v_pk_fma_f32 v[40:41], v[144:145], v[40:41], v[164:165]
	v_pk_fma_f32 v[42:43], v[146:147], v[42:43], v[166:167]
	s_add_u32 s98, s10, 0xa0000
	s_addc_u32 s99, s11, 0
	global_store_dwordx4 v203, v[40:43], s[98:99] offset:16
	s_waitcnt vmcnt(17)
	v_pk_fma_f32 v[12:13], v[156:157], v[12:13], v[168:169]
	v_pk_fma_f32 v[14:15], v[158:159], v[14:15], v[170:171]
	s_add_u32 s42, s10, 0xa0200
	s_addc_u32 s43, s11, 0
	global_store_dwordx4 v203, v[12:15], s[42:43]
	s_waitcnt vmcnt(16)
	v_pk_fma_f32 v[8:9], v[152:153], v[8:9], v[172:173]
	v_pk_fma_f32 v[10:11], v[154:155], v[10:11], v[174:175]
	s_add_u32 s98, s10, 0xa0200
	s_addc_u32 s99, s11, 0
	global_store_dwordx4 v203, v[8:11], s[98:99] offset:16
	s_waitcnt vmcnt(15)
	v_pk_fma_f32 v[36:37], v[148:149], v[36:37], v[176:177]
	v_pk_fma_f32 v[38:39], v[150:151], v[38:39], v[178:179]
	s_add_u32 s42, s10, 0xb0000
	s_addc_u32 s43, s11, 0
	global_store_dwordx4 v203, v[36:39], s[42:43]
	s_waitcnt vmcnt(14)
	v_pk_fma_f32 v[32:33], v[144:145], v[32:33], v[180:181]
	v_pk_fma_f32 v[34:35], v[146:147], v[34:35], v[182:183]
	s_add_u32 s98, s10, 0xb0000
	s_addc_u32 s99, s11, 0
	global_store_dwordx4 v203, v[32:35], s[98:99] offset:16
	s_waitcnt vmcnt(13)
	v_pk_fma_f32 v[4:5], v[156:157], v[4:5], v[206:207]
	v_pk_fma_f32 v[6:7], v[158:159], v[6:7], v[208:209]
	s_add_u32 s42, s10, 0xb0200
	s_addc_u32 s43, s11, 0
	global_store_dwordx4 v203, v[4:7], s[42:43]
	s_waitcnt vmcnt(12)
	v_pk_fma_f32 v[0:1], v[152:153], v[0:1], v[210:211]
	v_pk_fma_f32 v[2:3], v[154:155], v[2:3], v[212:213]
	s_add_u32 s98, s10, 0xb0200
	s_addc_u32 s99, s11, 0
	global_store_dwordx4 v203, v[0:3], s[98:99] offset:16
	s_branch .Lfq_predone
.Lfq_np1:
	s_add_u32 s42, s62, 0x0
	s_addc_u32 s43, s63, 0
	global_load_dwordx4 v[128:131], v205, s[42:43] sc0 sc1
	s_add_u32 s98, s62, 0x1000
	s_addc_u32 s99, s63, 0
	global_load_dwordx4 v[132:135], v205, s[98:99] sc0 sc1
	s_add_u32 s42, s62, 0x400
	s_addc_u32 s43, s63, 0
	global_load_dwordx4 v[136:139], v205, s[42:43] sc0 sc1
	s_add_u32 s98, s62, 0x1400
	s_addc_u32 s99, s63, 0
	global_load_dwordx4 v[140:143], v205, s[98:99] sc0 sc1
	s_add_u32 s42, s62, 0x800
	s_addc_u32 s43, s63, 0
	global_load_dwordx4 v[160:163], v205, s[42:43] sc0 sc1
	s_add_u32 s98, s62, 0x1800
	s_addc_u32 s99, s63, 0
	global_load_dwordx4 v[164:167], v205, s[98:99] sc0 sc1
	s_add_u32 s42, s62, 0xc00
	s_addc_u32 s43, s63, 0
	global_load_dwordx4 v[168:171], v205, s[42:43] sc0 sc1
	s_add_u32 s98, s62, 0x1c00
	s_addc_u32 s99, s63, 0
	global_load_dwordx4 v[172:175], v205, s[98:99] sc0 sc1
	s_add_u32 s42, s62, 0x2000
	s_addc_u32 s43, s63, 0
	global_load_dwordx4 v[176:179], v205, s[42:43] sc0 sc1
	s_add_u32 s98, s62, 0x3000
	s_addc_u32 s99, s63, 0
	global_load_dwordx4 v[180:183], v205, s[98:99] sc0 sc1
	s_add_u32 s42, s62, 0x2400
	s_addc_u32 s43, s63, 0
	global_load_dwordx4 v[206:209], v205, s[42:43] sc0 sc1
	s_add_u32 s98, s62, 0x3400
	s_addc_u32 s99, s63, 0
	global_load_dwordx4 v[210:213], v205, s[98:99] sc0 sc1
	s_add_u32 s42, s62, 0x2800
	s_addc_u32 s43, s63, 0
	global_load_dwordx4 v[236:239], v205, s[42:43] sc0 sc1
	s_waitcnt vmcnt(12)
	v_lshlrev_b32_e32 v240, 16, v128
	v_and_b32_e32 v241, 0xffff0000, v128
	v_pk_add_f32 v[124:125], v[124:125], v[240:241]
	v_lshlrev_b32_e32 v240, 16, v129
	v_and_b32_e32 v241, 0xffff0000, v129
	v_pk_add_f32 v[126:127], v[126:127], v[240:241]
	v_lshlrev_b32_e32 v240, 16, v130
	v_and_b32_e32 v241, 0xffff0000, v130
	v_pk_add_f32 v[120:121], v[120:121], v[240:241]
	v_lshlrev_b32_e32 v240, 16, v131
	v_and_b32_e32 v241, 0xffff0000, v131
	v_pk_add_f32 v[122:123], v[122:123], v[240:241]
	s_add_u32 s98, s62, 0x3800
	s_addc_u32 s99, s63, 0
	global_load_dwordx4 v[128:131], v205, s[98:99] sc0 sc1
	s_waitcnt vmcnt(12)
	v_lshlrev_b32_e32 v240, 16, v132
	v_and_b32_e32 v241, 0xffff0000, v132
	v_pk_add_f32 v[92:93], v[92:93], v[240:241]
	v_lshlrev_b32_e32 v240, 16, v133
	v_and_b32_e32 v241, 0xffff0000, v133
	v_pk_add_f32 v[94:95], v[94:95], v[240:241]
	v_lshlrev_b32_e32 v240, 16, v134
	v_and_b32_e32 v241, 0xffff0000, v134
	v_pk_add_f32 v[88:89], v[88:89], v[240:241]
	v_lshlrev_b32_e32 v240, 16, v135
	v_and_b32_e32 v241, 0xffff0000, v135
	v_pk_add_f32 v[90:91], v[90:91], v[240:241]
	s_add_u32 s42, s62, 0x2c00
	s_addc_u32 s43, s63, 0
	global_load_dwordx4 v[132:135], v205, s[42:43] sc0 sc1
	s_waitcnt vmcnt(12)
	v_lshlrev_b32_e32 v240, 16, v136
	v_and_b32_e32 v241, 0xffff0000, v136
	v_pk_add_f32 v[116:117], v[116:117], v[240:241]
	v_lshlrev_b32_e32 v240, 16, v137
	v_and_b32_e32 v241, 0xffff0000, v137
	v_pk_add_f32 v[118:119], v[118:119], v[240:241]
	v_lshlrev_b32_e32 v240, 16, v138
	v_and_b32_e32 v241, 0xffff0000, v138
	v_pk_add_f32 v[112:113], v[112:113], v[240:241]
	v_lshlrev_b32_e32 v240, 16, v139
	v_and_b32_e32 v241, 0xffff0000, v139
	v_pk_add_f32 v[114:115], v[114:115], v[240:241]
	s_add_u32 s98, s62, 0x3c00
	s_addc_u32 s99, s63, 0
	global_load_dwordx4 v[136:139], v205, s[98:99] sc0 sc1
	s_waitcnt vmcnt(12)
	v_lshlrev_b32_e32 v240, 16, v140
	v_and_b32_e32 v241, 0xffff0000, v140
	v_pk_add_f32 v[84:85], v[84:85], v[240:241]
	v_lshlrev_b32_e32 v240, 16, v141
	v_and_b32_e32 v241, 0xffff0000, v141
	v_pk_add_f32 v[86:87], v[86:87], v[240:241]
	v_lshlrev_b32_e32 v240, 16, v142
	v_and_b32_e32 v241, 0xffff0000, v142
	v_pk_add_f32 v[80:81], v[80:81], v[240:241]
	v_lshlrev_b32_e32 v240, 16, v143
	v_and_b32_e32 v241, 0xffff0000, v143
	v_pk_add_f32 v[82:83], v[82:83], v[240:241]
	s_add_u32 s42, s10, 0x0
	s_addc_u32 s43, s11, 0
	global_load_dwordx4 v[140:143], v203, s[42:43]
	s_waitcnt vmcnt(12)
	v_lshlrev_b32_e32 v240, 16, v160
	v_and_b32_e32 v241, 0xffff0000, v160
	v_pk_add_f32 v[108:109], v[108:109], v[240:241]
	v_lshlrev_b32_e32 v240, 16, v161
	v_and_b32_e32 v241, 0xffff0000, v161
	v_pk_add_f32 v[110:111], v[110:111], v[240:241]
	v_lshlrev_b32_e32 v240, 16, v162
	v_and_b32_e32 v241, 0xffff0000, v162
	v_pk_add_f32 v[104:105], v[104:105], v[240:241]
	v_lshlrev_b32_e32 v240, 16, v163
	v_and_b32_e32 v241, 0xffff0000, v163
	v_pk_add_f32 v[106:107], v[106:107], v[240:241]
	s_add_u32 s98, s10, 0x0
	s_addc_u32 s99, s11, 0
	global_load_dwordx4 v[160:163], v203, s[98:99] offset:16
	s_waitcnt vmcnt(12)
	v_lshlrev_b32_e32 v240, 16, v164
	v_and_b32_e32 v241, 0xffff0000, v164
	v_pk_add_f32 v[76:77], v[76:77], v[240:241]
	v_lshlrev_b32_e32 v240, 16, v165
	v_and_b32_e32 v241, 0xffff0000, v165
	v_pk_add_f32 v[78:79], v[78:79], v[240:241]
	v_lshlrev_b32_e32 v240, 16, v166
	v_and_b32_e32 v241, 0xffff0000, v166
	v_pk_add_f32 v[72:73], v[72:73], v[240:241]
	v_lshlrev_b32_e32 v240, 16, v167
	v_and_b32_e32 v241, 0xffff0000, v167
	v_pk_add_f32 v[74:75], v[74:75], v[240:241]
	s_add_u32 s42, s10, 0x200
	s_addc_u32 s43, s11, 0
	global_load_dwordx4 v[164:167], v203, s[42:43]
	s_waitcnt vmcnt(12)
	v_lshlrev_b32_e32 v240, 16, v168
	v_and_b32_e32 v241, 0xffff0000, v168
	v_pk_add_f32 v[100:101], v[100:101], v[240:241]
	v_lshlrev_b32_e32 v240, 16, v169
	v_and_b32_e32 v241, 0xffff0000, v169
	v_pk_add_f32 v[102:103], v[102:103], v[240:241]
	v_lshlrev_b32_e32 v240, 16, v170
	v_and_b32_e32 v241, 0xffff0000, v170
	v_pk_add_f32 v[96:97], v[96:97], v[240:241]
	v_lshlrev_b32_e32 v240, 16, v171
	v_and_b32_e32 v241, 0xffff0000, v171
	v_pk_add_f32 v[98:99], v[98:99], v[240:241]
	s_add_u32 s98, s10, 0x200
	s_addc_u32 s99, s11, 0
	global_load_dwordx4 v[168:171], v203, s[98:99] offset:16
	s_waitcnt vmcnt(12)
	v_lshlrev_b32_e32 v240, 16, v172
	v_and_b32_e32 v241, 0xffff0000, v172
	v_pk_add_f32 v[68:69], v[68:69], v[240:241]
	v_lshlrev_b32_e32 v240, 16, v173
	v_and_b32_e32 v241, 0xffff0000, v173
	v_pk_add_f32 v[70:71], v[70:71], v[240:241]
	v_lshlrev_b32_e32 v240, 16, v174
	v_and_b32_e32 v241, 0xffff0000, v174
	v_pk_add_f32 v[64:65], v[64:65], v[240:241]
	v_lshlrev_b32_e32 v240, 16, v175
	v_and_b32_e32 v241, 0xffff0000, v175
	v_pk_add_f32 v[66:67], v[66:67], v[240:241]
	s_add_u32 s42, s10, 0x10000
	s_addc_u32 s43, s11, 0
	global_load_dwordx4 v[172:175], v203, s[42:43]
	s_waitcnt vmcnt(12)
	v_lshlrev_b32_e32 v240, 16, v176
	v_and_b32_e32 v241, 0xffff0000, v176
	v_pk_add_f32 v[60:61], v[60:61], v[240:241]
	v_lshlrev_b32_e32 v240, 16, v177
	v_and_b32_e32 v241, 0xffff0000, v177
	v_pk_add_f32 v[62:63], v[62:63], v[240:241]
	v_lshlrev_b32_e32 v240, 16, v178
	v_and_b32_e32 v241, 0xffff0000, v178
	v_pk_add_f32 v[56:57], v[56:57], v[240:241]
	v_lshlrev_b32_e32 v240, 16, v179
	v_and_b32_e32 v241, 0xffff0000, v179
	v_pk_add_f32 v[58:59], v[58:59], v[240:241]
	s_add_u32 s98, s10, 0x10000
	s_addc_u32 s99, s11, 0
	global_load_dwordx4 v[176:179], v203, s[98:99] offset:16
	s_waitcnt vmcnt(12)
	v_lshlrev_b32_e32 v240, 16, v180
	v_and_b32_e32 v241, 0xffff0000, v180
	v_pk_add_f32 v[28:29], v[28:29], v[240:241]
	v_lshlrev_b32_e32 v240, 16, v181
	v_and_b32_e32 v241, 0xffff0000, v181
	v_pk_add_f32 v[30:31], v[30:31], v[240:241]
	v_lshlrev_b32_e32 v240, 16, v182
	v_and_b32_e32 v241, 0xffff0000, v182
	v_pk_add_f32 v[24:25], v[24:25], v[240:241]
	v_lshlrev_b32_e32 v240, 16, v183
	v_and_b32_e32 v241, 0xffff0000, v183
	v_pk_add_f32 v[26:27], v[26:27], v[240:241]
	s_add_u32 s42, s10, 0x10200
	s_addc_u32 s43, s11, 0
	global_load_dwordx4 v[180:183], v203, s[42:43]
	s_waitcnt vmcnt(12)
	v_lshlrev_b32_e32 v240, 16, v206
	v_and_b32_e32 v241, 0xffff0000, v206
	v_pk_add_f32 v[52:53], v[52:53], v[240:241]
	v_lshlrev_b32_e32 v240, 16, v207
	v_and_b32_e32 v241, 0xffff0000, v207
	v_pk_add_f32 v[54:55], v[54:55], v[240:241]
	v_lshlrev_b32_e32 v240, 16, v208
	v_and_b32_e32 v241, 0xffff0000, v208
	v_pk_add_f32 v[48:49], v[48:49], v[240:241]
	v_lshlrev_b32_e32 v240, 16, v209
	v_and_b32_e32 v241, 0xffff0000, v209
	v_pk_add_f32 v[50:51], v[50:51], v[240:241]
	s_add_u32 s98, s10, 0x10200
	s_addc_u32 s99, s11, 0
	global_load_dwordx4 v[206:209], v203, s[98:99] offset:16
	s_waitcnt vmcnt(12)
	v_lshlrev_b32_e32 v240, 16, v210
	v_and_b32_e32 v241, 0xffff0000, v210
	v_pk_add_f32 v[20:21], v[20:21], v[240:241]
	v_lshlrev_b32_e32 v240, 16, v211
	v_and_b32_e32 v241, 0xffff0000, v211
	v_pk_add_f32 v[22:23], v[22:23], v[240:241]
	v_lshlrev_b32_e32 v240, 16, v212
	v_and_b32_e32 v241, 0xffff0000, v212
	v_pk_add_f32 v[16:17], v[16:17], v[240:241]
	v_lshlrev_b32_e32 v240, 16, v213
	v_and_b32_e32 v241, 0xffff0000, v213
	v_pk_add_f32 v[18:19], v[18:19], v[240:241]
	s_add_u32 s42, s10, 0x20000
	s_addc_u32 s43, s11, 0
	global_load_dwordx4 v[210:213], v203, s[42:43]
	s_waitcnt vmcnt(12)
	v_lshlrev_b32_e32 v240, 16, v236
	v_and_b32_e32 v241, 0xffff0000, v236
	v_pk_add_f32 v[44:45], v[44:45], v[240:241]
	v_lshlrev_b32_e32 v240, 16, v237
	v_and_b32_e32 v241, 0xffff0000, v237
	v_pk_add_f32 v[46:47], v[46:47], v[240:241]
	v_lshlrev_b32_e32 v240, 16, v238
	v_and_b32_e32 v241, 0xffff0000, v238
	v_pk_add_f32 v[40:41], v[40:41], v[240:241]
	v_lshlrev_b32_e32 v240, 16, v239
	v_and_b32_e32 v241, 0xffff0000, v239
	v_pk_add_f32 v[42:43], v[42:43], v[240:241]
	s_add_u32 s98, s10, 0x20000
	s_addc_u32 s99, s11, 0
	global_load_dwordx4 v[236:239], v203, s[98:99] offset:16
	s_waitcnt vmcnt(12)
	v_lshlrev_b32_e32 v240, 16, v128
	v_and_b32_e32 v241, 0xffff0000, v128
	v_pk_add_f32 v[12:13], v[12:13], v[240:241]
	v_lshlrev_b32_e32 v240, 16, v129
	v_and_b32_e32 v241, 0xffff0000, v129
	v_pk_add_f32 v[14:15], v[14:15], v[240:241]
	v_lshlrev_b32_e32 v240, 16, v130
	v_and_b32_e32 v241, 0xffff0000, v130
	v_pk_add_f32 v[8:9], v[8:9], v[240:241]
	v_lshlrev_b32_e32 v240, 16, v131
	v_and_b32_e32 v241, 0xffff0000, v131
	v_pk_add_f32 v[10:11], v[10:11], v[240:241]
	s_add_u32 s42, s10, 0x20200
	s_addc_u32 s43, s11, 0
	global_load_dwordx4 v[128:131], v203, s[42:43]
	s_waitcnt vmcnt(12)
	v_lshlrev_b32_e32 v240, 16, v132
	v_and_b32_e32 v241, 0xffff0000, v132
	v_pk_add_f32 v[36:37], v[36:37], v[240:241]
	v_lshlrev_b32_e32 v240, 16, v133
	v_and_b32_e32 v241, 0xffff0000, v133
	v_pk_add_f32 v[38:39], v[38:39], v[240:241]
	v_lshlrev_b32_e32 v240, 16, v134
	v_and_b32_e32 v241, 0xffff0000, v134
	v_pk_add_f32 v[32:33], v[32:33], v[240:241]
	v_lshlrev_b32_e32 v240, 16, v135
	v_and_b32_e32 v241, 0xffff0000, v135
	v_pk_add_f32 v[34:35], v[34:35], v[240:241]
	s_add_u32 s98, s10, 0x20200
	s_addc_u32 s99, s11, 0
	global_load_dwordx4 v[132:135], v203, s[98:99] offset:16
	s_waitcnt vmcnt(12)
	v_lshlrev_b32_e32 v240, 16, v136
	v_and_b32_e32 v241, 0xffff0000, v136
	v_pk_add_f32 v[4:5], v[4:5], v[240:241]
	v_lshlrev_b32_e32 v240, 16, v137
	v_and_b32_e32 v241, 0xffff0000, v137
	v_pk_add_f32 v[6:7], v[6:7], v[240:241]
	v_lshlrev_b32_e32 v240, 16, v138
	v_and_b32_e32 v241, 0xffff0000, v138
	v_pk_add_f32 v[0:1], v[0:1], v[240:241]
	v_lshlrev_b32_e32 v240, 16, v139
	v_and_b32_e32 v241, 0xffff0000, v139
	v_pk_add_f32 v[2:3], v[2:3], v[240:241]
	s_add_u32 s42, s10, 0x30000
	s_addc_u32 s43, s11, 0
	global_load_dwordx4 v[136:139], v203, s[42:43]
	s_waitcnt vmcnt(12)
	v_pk_fma_f32 v[124:125], v[148:149], v[124:125], v[140:141]
	v_pk_fma_f32 v[126:127], v[150:151], v[126:127], v[142:143]
	s_add_u32 s98, s10, 0x0
	s_addc_u32 s99, s11, 0
	global_store_dwordx4 v203, v[124:127], s[98:99]
	s_add_u32 s42, s10, 0x30000
	s_addc_u32 s43, s11, 0
	global_load_dwordx4 v[140:143], v203, s[42:43] offset:16
	s_waitcnt vmcnt(13)
	v_pk_fma_f32 v[120:121], v[144:145], v[120:121], v[160:161]
	v_pk_fma_f32 v[122:123], v[146:147], v[122:123], v[162:163]
	s_add_u32 s98, s10, 0x0
	s_addc_u32 s99, s11, 0
	global_store_dwordx4 v203, v[120:123], s[98:99] offset:16
	s_add_u32 s42, s10, 0x30200
	s_addc_u32 s43, s11, 0
	global_load_dwordx4 v[160:163], v203, s[42:43]
	s_waitcnt vmcnt(14)
	v_pk_fma_f32 v[92:93], v[156:157], v[92:93], v[164:165]
	v_pk_fma_f32 v[94:95], v[158:159], v[94:95], v[166:167]
	s_add_u32 s98, s10, 0x200
	s_addc_u32 s99, s11, 0
	global_store_dwordx4 v203, v[92:95], s[98:99]
	s_add_u32 s42, s10, 0x30200
	s_addc_u32 s43, s11, 0
	global_load_dwordx4 v[164:167], v203, s[42:43] offset:16
	s_waitcnt vmcnt(15)
	v_pk_fma_f32 v[88:89], v[152:153], v[88:89], v[168:169]
	v_pk_fma_f32 v[90:91], v[154:155], v[90:91], v[170:171]
	s_add_u32 s98, s10, 0x200
	s_addc_u32 s99, s11, 0
	global_store_dwordx4 v203, v[88:91], s[98:99] offset:16
	s_add_u32 s42, s10, 0x80000
	s_addc_u32 s43, s11, 0
	global_load_dwordx4 v[168:171], v203, s[42:43]
	s_waitcnt vmcnt(16)
	v_pk_fma_f32 v[116:117], v[148:149], v[116:117], v[172:173]
	v_pk_fma_f32 v[118:119], v[150:151], v[118:119], v[174:175]
	s_add_u32 s98, s10, 0x10000
	s_addc_u32 s99, s11, 0
	global_store_dwordx4 v203, v[116:119], s[98:99]
	s_add_u32 s42, s10, 0x80000
	s_addc_u32 s43, s11, 0
	global_load_dwordx4 v[172:175], v203, s[42:43] offset:16
	s_waitcnt vmcnt(17)
	v_pk_fma_f32 v[112:113], v[144:145], v[112:113], v[176:177]
	v_pk_fma_f32 v[114:115], v[146:147], v[114:115], v[178:179]
	s_add_u32 s98, s10, 0x10000
	s_addc_u32 s99, s11, 0
	global_store_dwordx4 v203, v[112:115], s[98:99] offset:16
	s_add_u32 s42, s10, 0x80200
	s_addc_u32 s43, s11, 0
	global_load_dwordx4 v[176:179], v203, s[42:43]
	s_waitcnt vmcnt(18)
	v_pk_fma_f32 v[84:85], v[156:157], v[84:85], v[180:181]
	v_pk_fma_f32 v[86:87], v[158:159], v[86:87], v[182:183]
	s_add_u32 s98, s10, 0x10200
	s_addc_u32 s99, s11, 0
	global_store_dwordx4 v203, v[84:87], s[98:99]
	s_add_u32 s42, s10, 0x80200
	s_addc_u32 s43, s11, 0
	global_load_dwordx4 v[180:183], v203, s[42:43] offset:16
	s_waitcnt vmcnt(19)
	v_pk_fma_f32 v[80:81], v[152:153], v[80:81], v[206:207]
	v_pk_fma_f32 v[82:83], v[154:155], v[82:83], v[208:209]
	s_add_u32 s98, s10, 0x10200
	s_addc_u32 s99, s11, 0
	global_store_dwordx4 v203, v[80:83], s[98:99] offset:16
	s_add_u32 s42, s10, 0x90000
	s_addc_u32 s43, s11, 0
	global_load_dwordx4 v[206:209], v203, s[42:43]
	s_waitcnt vmcnt(20)
	v_pk_fma_f32 v[108:109], v[148:149], v[108:109], v[210:211]
	v_pk_fma_f32 v[110:111], v[150:151], v[110:111], v[212:213]
	s_add_u32 s98, s10, 0x20000
	s_addc_u32 s99, s11, 0
	global_store_dwordx4 v203, v[108:111], s[98:99]
	s_add_u32 s42, s10, 0x90000
	s_addc_u32 s43, s11, 0
	global_load_dwordx4 v[210:213], v203, s[42:43] offset:16
	s_waitcnt vmcnt(21)
	v_pk_fma_f32 v[104:105], v[144:145], v[104:105], v[236:237]
	v_pk_fma_f32 v[106:107], v[146:147], v[106:107], v[238:239]
	s_add_u32 s98, s10, 0x20000
	s_addc_u32 s99, s11, 0
	global_store_dwordx4 v203, v[104:107], s[98:99] offset:16
	s_add_u32 s42, s10, 0x90200
	s_addc_u32 s43, s11, 0
	global_load_dwordx4 v[236:239], v203, s[42:43]
	s_waitcnt vmcnt(22)
	v_pk_fma_f32 v[76:77], v[156:157], v[76:77], v[128:129]
	v_pk_fma_f32 v[78:79], v[158:159], v[78:79], v[130:131]
	s_add_u32 s98, s10, 0x20200
	s_addc_u32 s99, s11, 0
	global_store_dwordx4 v203, v[76:79], s[98:99]
	s_add_u32 s42, s10, 0x90200
	s_addc_u32 s43, s11, 0
	global_load_dwordx4 v[128:131], v203, s[42:43] offset:16
	s_waitcnt vmcnt(23)
	v_pk_fma_f32 v[72:73], v[152:153], v[72:73], v[132:133]
	v_pk_fma_f32 v[74:75], v[154:155], v[74:75], v[134:135]
	s_add_u32 s98, s10, 0x20200
	s_addc_u32 s99, s11, 0
	global_store_dwordx4 v203, v[72:75], s[98:99] offset:16
	s_add_u32 s42, s10, 0xa0000
	s_addc_u32 s43, s11, 0
	global_load_dwordx4 v[132:135], v203, s[42:43]
	s_waitcnt vmcnt(24)
	v_pk_fma_f32 v[100:101], v[148:149], v[100:101], v[136:137]
	v_pk_fma_f32 v[102:103], v[150:151], v[102:103], v[138:139]
	s_add_u32 s98, s10, 0x30000
	s_addc_u32 s99, s11, 0
	global_store_dwordx4 v203, v[100:103], s[98:99]
	s_add_u32 s42, s10, 0xa0000
	s_addc_u32 s43, s11, 0
	global_load_dwordx4 v[136:139], v203, s[42:43] offset:16
	s_waitcnt vmcnt(24)
	v_pk_fma_f32 v[96:97], v[144:145], v[96:97], v[140:141]
	v_pk_fma_f32 v[98:99], v[146:147], v[98:99], v[142:143]
	s_add_u32 s98, s10, 0x30000
	s_addc_u32 s99, s11, 0
	global_store_dwordx4 v203, v[96:99], s[98:99] offset:16
	s_add_u32 s42, s10, 0xa0200
	s_addc_u32 s43, s11, 0
	global_load_dwordx4 v[140:143], v203, s[42:43]
	s_waitcnt vmcnt(24)
	v_pk_fma_f32 v[68:69], v[156:157], v[68:69], v[160:161]
	v_pk_fma_f32 v[70:71], v[158:159], v[70:71], v[162:163]
	s_add_u32 s98, s10, 0x30200
	s_addc_u32 s99, s11, 0
	global_store_dwordx4 v203, v[68:71], s[98:99]
	s_add_u32 s42, s10, 0xa0200
	s_addc_u32 s43, s11, 0
	global_load_dwordx4 v[160:163], v203, s[42:43] offset:16
	s_waitcnt vmcnt(24)
	v_pk_fma_f32 v[64:65], v[152:153], v[64:65], v[164:165]
	v_pk_fma_f32 v[66:67], v[154:155], v[66:67], v[166:167]
	s_add_u32 s98, s10, 0x30200
	s_addc_u32 s99, s11, 0
	global_store_dwordx4 v203, v[64:67], s[98:99] offset:16
	s_add_u32 s42, s10, 0xb0000
	s_addc_u32 s43, s11, 0
	global_load_dwordx4 v[164:167], v203, s[42:43]
	s_waitcnt vmcnt(24)
	v_pk_fma_f32 v[60:61], v[148:149], v[60:61], v[168:169]
	v_pk_fma_f32 v[62:63], v[150:151], v[62:63], v[170:171]
	s_add_u32 s98, s10, 0x80000
	s_addc_u32 s99, s11, 0
	global_store_dwordx4 v203, v[60:63], s[98:99]
	s_add_u32 s42, s10, 0xb0000
	s_addc_u32 s43, s11, 0
	global_load_dwordx4 v[168:171], v203, s[42:43] offset:16
	s_waitcnt vmcnt(24)
	v_pk_fma_f32 v[56:57], v[144:145], v[56:57], v[172:173]
	v_pk_fma_f32 v[58:59], v[146:147], v[58:59], v[174:175]
	s_add_u32 s98, s10, 0x80000
	s_addc_u32 s99, s11, 0
	global_store_dwordx4 v203, v[56:59], s[98:99] offset:16
	s_add_u32 s42, s10, 0xb0200
	s_addc_u32 s43, s11, 0
	global_load_dwordx4 v[172:175], v203, s[42:43]
	s_waitcnt vmcnt(24)
	v_pk_fma_f32 v[28:29], v[156:157], v[28:29], v[176:177]
	v_pk_fma_f32 v[30:31], v[158:159], v[30:31], v[178:179]
	s_add_u32 s98, s10, 0x80200
	s_addc_u32 s99, s11, 0
	global_store_dwordx4 v203, v[28:31], s[98:99]
	s_add_u32 s42, s10, 0xb0200
	s_addc_u32 s43, s11, 0
	global_load_dwordx4 v[176:179], v203, s[42:43] offset:16
	s_waitcnt vmcnt(24)
	v_pk_fma_f32 v[24:25], v[152:153], v[24:25], v[180:181]
	v_pk_fma_f32 v[26:27], v[154:155], v[26:27], v[182:183]
	s_add_u32 s98, s10, 0x80200
	s_addc_u32 s99, s11, 0
	global_store_dwordx4 v203, v[24:27], s[98:99] offset:16
	s_waitcnt vmcnt(23)
	v_pk_fma_f32 v[52:53], v[148:149], v[52:53], v[206:207]
	v_pk_fma_f32 v[54:55], v[150:151], v[54:55], v[208:209]
	s_add_u32 s42, s10, 0x90000
	s_addc_u32 s43, s11, 0
	global_store_dwordx4 v203, v[52:55], s[42:43]
	s_waitcnt vmcnt(22)
	v_pk_fma_f32 v[48:49], v[144:145], v[48:49], v[210:211]
	v_pk_fma_f32 v[50:51], v[146:147], v[50:51], v[212:213]
	s_add_u32 s98, s10, 0x90000
	s_addc_u32 s99, s11, 0
	global_store_dwordx4 v203, v[48:51], s[98:99] offset:16
	s_waitcnt vmcnt(21)
	v_pk_fma_f32 v[20:21], v[156:157], v[20:21], v[236:237]
	v_pk_fma_f32 v[22:23], v[158:159], v[22:23], v[238:239]
	s_add_u32 s42, s10, 0x90200
	s_addc_u32 s43, s11, 0
	global_store_dwordx4 v203, v[20:23], s[42:43]
	s_waitcnt vmcnt(20)
	v_pk_fma_f32 v[16:17], v[152:153], v[16:17], v[128:129]
	v_pk_fma_f32 v[18:19], v[154:155], v[18:19], v[130:131]
	s_add_u32 s98, s10, 0x90200
	s_addc_u32 s99, s11, 0
	global_store_dwordx4 v203, v[16:19], s[98:99] offset:16
	s_waitcnt vmcnt(19)
	v_pk_fma_f32 v[44:45], v[148:149], v[44:45], v[132:133]
	v_pk_fma_f32 v[46:47], v[150:151], v[46:47], v[134:135]
	s_add_u32 s42, s10, 0xa0000
	s_addc_u32 s43, s11, 0
	global_store_dwordx4 v203, v[44:47], s[42:43]
	s_waitcnt vmcnt(18)
	v_pk_fma_f32 v[40:41], v[144:145], v[40:41], v[136:137]
	v_pk_fma_f32 v[42:43], v[146:147], v[42:43], v[138:139]
	s_add_u32 s98, s10, 0xa0000
	s_addc_u32 s99, s11, 0
	global_store_dwordx4 v203, v[40:43], s[98:99] offset:16
	s_waitcnt vmcnt(17)
	v_pk_fma_f32 v[12:13], v[156:157], v[12:13], v[140:141]
	v_pk_fma_f32 v[14:15], v[158:159], v[14:15], v[142:143]
	s_add_u32 s42, s10, 0xa0200
	s_addc_u32 s43, s11, 0
	global_store_dwordx4 v203, v[12:15], s[42:43]
	s_waitcnt vmcnt(16)
	v_pk_fma_f32 v[8:9], v[152:153], v[8:9], v[160:161]
	v_pk_fma_f32 v[10:11], v[154:155], v[10:11], v[162:163]
	s_add_u32 s98, s10, 0xa0200
	s_addc_u32 s99, s11, 0
	global_store_dwordx4 v203, v[8:11], s[98:99] offset:16
	s_waitcnt vmcnt(15)
	v_pk_fma_f32 v[36:37], v[148:149], v[36:37], v[164:165]
	v_pk_fma_f32 v[38:39], v[150:151], v[38:39], v[166:167]
	s_add_u32 s42, s10, 0xb0000
	s_addc_u32 s43, s11, 0
	global_store_dwordx4 v203, v[36:39], s[42:43]
	s_waitcnt vmcnt(14)
	v_pk_fma_f32 v[32:33], v[144:145], v[32:33], v[168:169]
	v_pk_fma_f32 v[34:35], v[146:147], v[34:35], v[170:171]
	s_add_u32 s98, s10, 0xb0000
	s_addc_u32 s99, s11, 0
	global_store_dwordx4 v203, v[32:35], s[98:99] offset:16
	s_waitcnt vmcnt(13)
	v_pk_fma_f32 v[4:5], v[156:157], v[4:5], v[172:173]
	v_pk_fma_f32 v[6:7], v[158:159], v[6:7], v[174:175]
	s_add_u32 s42, s10, 0xb0200
	s_addc_u32 s43, s11, 0
	global_store_dwordx4 v203, v[4:7], s[42:43]
	s_waitcnt vmcnt(12)
	v_pk_fma_f32 v[0:1], v[152:153], v[0:1], v[176:177]
	v_pk_fma_f32 v[2:3], v[154:155], v[2:3], v[178:179]
	s_add_u32 s98, s10, 0xb0200
	s_addc_u32 s99, s11, 0
	global_store_dwordx4 v203, v[0:3], s[98:99] offset:16
.Lfq_predone:
	s_and_b64 vcc, exec, s[80:81]
	s_cbranch_vccnz .Lfq_noq
	v_lshlrev_b64 v[160:161], 2, v[200:201]
	v_lshl_add_u64 v[160:161], s[16:17], 0, v[160:161]
	v_lshl_add_u64 v[160:161], v[160:161], 0, s[36:37]
	global_load_dwordx4 v[140:143], v[160:161], off
	global_load_dwordx4 v[136:139], v[160:161], off offset:16
	global_load_dwordx4 v[132:135], v[160:161], off offset:512
	global_load_dwordx4 v[128:131], v[160:161], off offset:528
